# attention step packed adds split; barrier: workgroups poll the cross-XCD release word; Wo-phase rstd table loads all in flight
# speedup vs baseline: 1.0067x; 1.0020x over previous
.LBB0_137:
	s_or_b64 exec, exec, s[8:9]
	v_cvt_f32_u32_e32 v4, v2
	s_waitcnt vmcnt(0)
	v_readfirstlane_b32 s6, v3
	v_sub_u32_e32 v3, 0, v2
	v_rcp_iflag_f32_e32 v4, v4
	v_add_u32_e32 v5, s6, v1
	v_mul_f32_e32 v4, 0x4f7ffffe, v4
	v_cvt_u32_f32_e32 v4, v4
	v_mul_lo_u32 v1, v3, v4
	v_mul_hi_u32 v1, v4, v1
	v_add_u32_e32 v1, v4, v1
	v_mul_hi_u32 v1, v5, v1
	v_mul_lo_u32 v3, v1, v2
	v_sub_u32_e32 v3, v5, v3
	v_add_u32_e32 v4, 1, v1
	v_cmp_ge_u32_e32 vcc, v3, v2
	s_nop 1
	v_cndmask_b32_e32 v1, v1, v4, vcc
	v_sub_u32_e32 v4, v3, v2
	v_cndmask_b32_e32 v3, v3, v4, vcc
	v_add_u32_e32 v4, 1, v1
	v_cmp_ge_u32_e32 vcc, v3, v2
	v_add_u32_e32 v3, 1, v5
	s_nop 0
	v_cndmask_b32_e32 v1, v1, v4, vcc
	v_mul_lo_u32 v4, v2, v1
	v_add_u32_e32 v2, v4, v2
	v_cmp_ne_u32_e32 vcc, v3, v2
	s_and_saveexec_b64 s[6:7], vcc
	s_xor_b64 s[6:7], exec, s[6:7]
	s_cbranch_execz .LBB0_151
	s_waitcnt lgkmcnt(0)
	v_mov_b32_e32 v0, 0xf3500
	global_load_dword v0, v0, s[80:81] sc1
	s_add_u32 s12, s80, 0xf3500
	s_addc_u32 s13, s81, 0
	s_waitcnt vmcnt(0)
	v_cmp_eq_u32_e32 vcc, v0, v1
	s_and_saveexec_b64 s[8:9], vcc
	s_cbranch_execz .LBB0_150
	s_add_u32 s10, s80, 0xf0200
	s_addc_u32 s11, s81, 0
	s_mov_b32 s24, 1
	s_mov_b64 s[14:15], 0
	v_mov_b32_e32 v0, 0
	s_branch .LBB0_141

.LBB0_168:
	s_or_b64 exec, exec, s[6:7]
	s_mov_b64 s[6:7], exec
	v_mbcnt_lo_u32_b32 v0, s6, 0
	v_mbcnt_hi_u32_b32 v0, s7, v0
	v_cmp_eq_u32_e32 vcc, 0, v0
	s_waitcnt vmcnt(0)
	buffer_inv sc1
	s_and_saveexec_b64 s[8:9], vcc
	s_cbranch_execz .LBB0_170
	s_bcnt1_i32_b64 s6, s[6:7]
	v_mov_b32_e32 v0, 0x2000
	v_mov_b32_e32 v1, s6
.LBB0_170:
	s_or_b64 exec, exec, s[8:9]
	s_waitcnt vmcnt(0)

.LBB0_247:
	s_or_b64 exec, exec, s[6:7]
	s_mov_b64 s[6:7], exec
	v_mbcnt_lo_u32_b32 v0, s6, 0
	v_mbcnt_hi_u32_b32 v0, s7, v0
	v_cmp_eq_u32_e32 vcc, 0, v0
	s_waitcnt vmcnt(0)
	buffer_inv sc1
	s_and_saveexec_b64 s[8:9], vcc
	s_cbranch_execz .LBB0_249
	s_bcnt1_i32_b64 s6, s[6:7]
	v_mov_b32_e32 v0, 0x2000
	v_mov_b32_e32 v1, s6
.LBB0_249:
	s_or_b64 exec, exec, s[8:9]
	s_waitcnt vmcnt(0)

.LBB0_374:
	s_or_b64 exec, exec, s[6:7]
	s_mov_b64 s[6:7], exec
	v_mbcnt_lo_u32_b32 v0, s6, 0
	v_mbcnt_hi_u32_b32 v0, s7, v0
	v_cmp_eq_u32_e32 vcc, 0, v0
	s_waitcnt vmcnt(0)
	buffer_inv sc1
	s_and_saveexec_b64 s[8:9], vcc
	s_cbranch_execz .LBB0_376
	s_bcnt1_i32_b64 s6, s[6:7]
	v_mov_b32_e32 v0, 0x2000
	v_mov_b32_e32 v1, s6
.LBB0_376:
	s_or_b64 exec, exec, s[8:9]
	s_waitcnt vmcnt(0)

.LBB0_405:
	s_add_i32 s72, s60, -3
	s_cmp_ge_u32 s72, s38
	s_cselect_b64 s[68:69], -1, 0
	s_cmp_lt_u32 s72, s39
	s_cselect_b64 vcc, -1, 0
	s_and_b64 s[68:69], s[68:69], vcc
	s_andn2_b64 vcc, exec, s[68:69]
	s_cbranch_vccnz .LBB0_407
	v_add_u32_e32 v178, v150, v149
	v_add_u32_e32 v181, 0x2000, v178
	v_add_u32_e32 v218, 0x2800, v178
	v_add_u32_e32 v219, 0x3000, v178
	v_add_u32_e32 v178, v150, v151
	v_add_u32_e32 v119, v148, v149
	v_add_u32_e32 v136, s70, v152
	v_add_u32_sdwa v163, s70, v143 dst_sel:DWORD dst_unused:UNUSED_PAD src0_sel:DWORD src1_sel:BYTE_2
	v_add_u32_sdwa v165, s70, v143 dst_sel:DWORD dst_unused:UNUSED_PAD src0_sel:DWORD src1_sel:BYTE_3
	v_add_u32_e32 v220, 0x2000, v178
	v_add_u32_sdwa v179, s70, v141 dst_sel:DWORD dst_unused:UNUSED_PAD src0_sel:DWORD src1_sel:BYTE_1
	ds_read_b128 v[158:161], v119
	ds_read_b128 v[166:169], v119 offset:64
	ds_read_b128 v[170:173], v119 offset:2304
	ds_read_b128 v[174:177], v119 offset:2368
	v_add_u32_e32 v162, s70, v153
	ds_read2_b64 v[182:185], v181 offset0:128 offset1:132
	ds_read2_b64 v[186:189], v218 offset0:160 offset1:164
	ds_read2_b64 v[190:193], v219 offset0:192 offset1:196
	ds_read2_b64 v[194:197], v220 offset0:128 offset1:132
	ds_read_b128 v[198:201], v119 offset:1152
	ds_read_b128 v[202:205], v119 offset:1216
	ds_read_b128 v[206:209], v119 offset:3456
	ds_read_b128 v[210:213], v119 offset:3520
	v_add_u32_e32 v178, s70, v155
	v_add_u32_sdwa v214, s70, v142 dst_sel:DWORD dst_unused:UNUSED_PAD src0_sel:DWORD src1_sel:BYTE_2
	v_add_u32_sdwa v215, s70, v142 dst_sel:DWORD dst_unused:UNUSED_PAD src0_sel:DWORD src1_sel:BYTE_3
	ds_read_b32 v136, v136 offset:41856
	ds_read_b32 v216, v162 offset:41856
	ds_read_b32 v163, v163 offset:41856
	ds_read_b32 v165, v165 offset:41856
	ds_read_b32 v217, v178 offset:41856
	ds_read_b32 v179, v179 offset:41856
	ds_read_b32 v221, v214 offset:41856
	ds_read_b32 v222, v215 offset:41856
	s_setprio 1
	s_waitcnt vmcnt(7) lgkmcnt(14)
	v_mfma_f32_16x16x32_bf16 v[158:161], v[158:161], v[80:83], 0
	s_waitcnt vmcnt(6)
	v_mfma_f32_16x16x32_bf16 v[158:161], v[166:169], v[84:87], v[158:161]
	v_mfma_f32_16x16x32_bf16 v[166:169], v[170:173], v[80:83], 0
	v_mfma_f32_16x16x32_bf16 v[166:169], v[174:177], v[84:87], v[166:169]
	s_setprio 0
	s_nop 6
	v_cndmask_b32_e64 v158, v166, v158, s[20:21]
	s_waitcnt lgkmcnt(7)
	v_add_f32_e32 v136, v136, v158
	v_exp_f32_e32 v162, v136
	v_cndmask_b32_e64 v136, v159, v167, s[10:11]
	v_cndmask_b32_e64 v159, v160, v168, s[12:13]
	s_waitcnt lgkmcnt(5)
	v_add_f32_e32 v159, v163, v159
	v_add_f32_e32 v136, v216, v136
	v_exp_f32_e32 v214, v159
	v_cndmask_b32_e64 v159, v161, v169, s[14:15]
	v_exp_f32_e32 v178, v136
	s_waitcnt lgkmcnt(4)
	v_add_f32_e32 v159, v165, v159
	v_exp_f32_e32 v216, v159
	v_cndmask_b32_e64 v159, v214, 0, s[12:13]
	v_cndmask_b32_e64 v158, v178, 0, s[10:11]
	v_cndmask_b32_e64 v160, 0, v178, s[10:11]
	v_cndmask_b32_e64 v161, 0, v214, s[12:13]
	v_cndmask_b32_e64 v136, 0, v162, s[20:21]
	v_cndmask_b32_e64 v166, v162, 0, s[20:21]
	v_cndmask_b32_e64 v163, v216, 0, s[14:15]
	v_cndmask_b32_e64 v165, 0, v216, s[14:15]
	v_cvt_pk_bf16_f32 v158, v136, v158
	v_cvt_pk_bf16_f32 v159, v159, v163
	v_cvt_pk_bf16_f32 v160, v166, v160
	v_cvt_pk_bf16_f32 v161, v161, v165
	s_setprio 1
	v_mfma_f32_16x16x32_bf16 v[60:63], v[182:185], v[158:161], v[60:63]
	v_mfma_f32_16x16x32_bf16 v[56:59], v[186:189], v[158:161], v[56:59]
	v_mfma_f32_16x16x32_bf16 v[52:55], v[190:193], v[158:161], v[52:55]
	v_mfma_f32_16x16x32_bf16 v[48:51], v[194:197], v[158:161], v[48:51]
	s_setprio 0
	ds_read2_b64 v[158:161], v181 offset0:130 offset1:134
	ds_read2_b64 v[166:169], v218 offset0:162 offset1:166
	ds_read2_b64 v[170:173], v219 offset0:194 offset1:198
	ds_read2_b64 v[174:177], v220 offset0:130 offset1:134
	ds_read_b128 v[182:185], v119 offset:3456
	ds_read_b128 v[186:189], v119 offset:3520
	ds_read_b128 v[190:193], v119 offset:5760
	ds_read_b128 v[194:197], v119 offset:5824
	v_add_u32_e32 v136, s70, v156
	v_add_u32_sdwa v165, s70, v140 dst_sel:DWORD dst_unused:UNUSED_PAD src0_sel:DWORD src1_sel:BYTE_2
	v_add_u32_sdwa v163, s70, v139 dst_sel:DWORD dst_unused:UNUSED_PAD src0_sel:DWORD src1_sel:BYTE_1
	v_add_u32_sdwa v215, s70, v140 dst_sel:DWORD dst_unused:UNUSED_PAD src0_sel:DWORD src1_sel:BYTE_3
	ds_read_b32 v136, v136 offset:41856
	ds_read_b32 v223, v163 offset:41856
	ds_read_b32 v165, v165 offset:41856
	ds_read_b32 v224, v215 offset:41856
	s_setprio 1
	s_waitcnt vmcnt(5)
	v_mfma_f32_16x16x32_bf16 v[198:201], v[198:201], v[88:91], 0
	s_waitcnt vmcnt(4)
	v_mfma_f32_16x16x32_bf16 v[198:201], v[202:205], v[92:95], v[198:201]
	v_mfma_f32_16x16x32_bf16 v[202:205], v[206:209], v[88:91], 0
	v_mfma_f32_16x16x32_bf16 v[202:205], v[210:213], v[92:95], v[202:205]
	s_setprio 0
	s_nop 6
	v_cndmask_b32_e64 v163, v198, v202, s[16:17]
	s_waitcnt lgkmcnt(14)
	v_add_f32_e32 v163, v217, v163
	v_cndmask_b32_e64 v198, v199, v203, s[18:19]
	v_cndmask_b32_e64 v200, v200, v204, s[6:7]
	v_exp_f32_e32 v163, v163
	v_add_f32_e32 v179, v179, v198
	s_waitcnt lgkmcnt(13)
	v_add_f32_e32 v200, v221, v200
	v_exp_f32_e32 v179, v179
	v_exp_f32_e32 v215, v200
	v_cndmask_b32_e64 v200, v201, v205, s[8:9]
	s_waitcnt lgkmcnt(12)
	v_add_f32_e32 v200, v222, v200
	v_exp_f32_e32 v217, v200
	v_cndmask_b32_e64 v198, v163, 0, s[16:17]
	v_cndmask_b32_e64 v202, 0, v163, s[16:17]
	v_add_f32_e32 v162, 0, v162
	v_add_f32_e32 v163, 0, v163
	v_cndmask_b32_e64 v199, v179, 0, s[18:19]
	v_add_f32_e32 v162, v178, v162
	v_add_f32_e32 v163, v179, v163
	v_cndmask_b32_e64 v200, 0, v179, s[18:19]
	v_add_f32_e32 v162, v214, v162
	v_add_f32_e32 v163, v215, v163
	v_cndmask_b32_e64 v201, v215, 0, s[6:7]
	v_add_f32_e32 v162, v216, v162
	v_add_f32_e32 v163, v217, v163
	v_cndmask_b32_e64 v203, 0, v215, s[6:7]
	v_add_f32_e32 v130, v130, v162
	v_add_f32_e32 v131, v131, v163
	v_cndmask_b32_e64 v204, v217, 0, s[8:9]
	v_cndmask_b32_e64 v205, 0, v217, s[8:9]
	v_cvt_pk_bf16_f32 v198, v198, v199
	v_cvt_pk_bf16_f32 v199, v201, v204
	v_cvt_pk_bf16_f32 v200, v202, v200
	v_cvt_pk_bf16_f32 v201, v203, v205
	s_setprio 1
	s_waitcnt lgkmcnt(11)
	v_mfma_f32_16x16x32_bf16 v[44:47], v[158:161], v[198:201], v[44:47]
	s_waitcnt lgkmcnt(10)
	v_mfma_f32_16x16x32_bf16 v[40:43], v[166:169], v[198:201], v[40:43]
	s_waitcnt lgkmcnt(9)
	v_mfma_f32_16x16x32_bf16 v[36:39], v[170:173], v[198:201], v[36:39]
	s_waitcnt lgkmcnt(8)
	v_mfma_f32_16x16x32_bf16 v[32:35], v[174:177], v[198:201], v[32:35]
	s_setprio 0
	ds_read2_b64 v[158:161], v181 offset0:134 offset1:138
	ds_read2_b64 v[166:169], v218 offset0:166 offset1:170
	ds_read2_b64 v[170:173], v219 offset0:198 offset1:202
	ds_read2_b64 v[174:177], v220 offset0:134 offset1:138
	ds_read_b128 v[198:201], v119 offset:4608
	ds_read_b128 v[202:205], v119 offset:4672
	v_add_u32_e32 v119, v148, v151
	ds_read_b128 v[206:209], v119
	ds_read_b128 v[210:213], v119 offset:64
	v_add_u32_e32 v119, s70, v154
	v_add_u32_sdwa v162, s70, v144 dst_sel:DWORD dst_unused:UNUSED_PAD src0_sel:DWORD src1_sel:BYTE_1
	v_add_u32_sdwa v163, s70, v145 dst_sel:DWORD dst_unused:UNUSED_PAD src0_sel:DWORD src1_sel:BYTE_2
	v_add_u32_sdwa v178, s70, v145 dst_sel:DWORD dst_unused:UNUSED_PAD src0_sel:DWORD src1_sel:BYTE_3
	ds_read_b32 v119, v119 offset:41856
	ds_read_b32 v179, v162 offset:41856
	ds_read_b32 v214, v163 offset:41856
	ds_read_b32 v215, v178 offset:41856
	s_setprio 1
	s_waitcnt vmcnt(3) lgkmcnt(14)
	v_mfma_f32_16x16x32_bf16 v[182:185], v[182:185], v[96:99], 0
	s_waitcnt vmcnt(2)
	v_mfma_f32_16x16x32_bf16 v[182:185], v[186:189], v[100:103], v[182:185]
	v_mfma_f32_16x16x32_bf16 v[186:189], v[190:193], v[96:99], 0
	v_mfma_f32_16x16x32_bf16 v[186:189], v[194:197], v[100:103], v[186:189]
	s_setprio 0
	s_nop 6
	v_cndmask_b32_e64 v162, v186, v182, s[2:3]
	v_add_f32_e32 v136, v136, v162
	v_exp_f32_e32 v162, v136
	v_cndmask_b32_e64 v136, v187, v183, s[4:5]
	v_cndmask_b32_e64 v183, v184, v188, s[22:23]
	s_waitcnt lgkmcnt(13)
	v_add_f32_e32 v165, v165, v183
	v_exp_f32_e32 v190, v165
	v_cndmask_b32_e64 v165, v185, v189, s[24:25]
	v_add_f32_e32 v136, v223, v136
	s_waitcnt lgkmcnt(12)
	v_add_f32_e32 v165, v224, v165
	v_exp_f32_e32 v178, v136
	v_exp_f32_e32 v192, v165
	v_cndmask_b32_e64 v183, v190, 0, s[22:23]
	v_cndmask_b32_e64 v185, 0, v190, s[22:23]
	v_cndmask_b32_e64 v182, 0, v178, s[4:5]
	v_cndmask_b32_e64 v184, v192, 0, s[24:25]
	v_cndmask_b32_e64 v136, 0, v162, s[2:3]
	v_cndmask_b32_e64 v163, v162, 0, s[2:3]
	v_cndmask_b32_e64 v165, v178, 0, s[4:5]
	v_cndmask_b32_e64 v186, 0, v192, s[24:25]
	v_cvt_pk_bf16_f32 v182, v136, v182
	v_cvt_pk_bf16_f32 v183, v183, v184
	v_cvt_pk_bf16_f32 v184, v163, v165
	v_cvt_pk_bf16_f32 v185, v185, v186
	s_setprio 1
	s_waitcnt lgkmcnt(11)
	v_mfma_f32_16x16x32_bf16 v[28:31], v[158:161], v[182:185], v[28:31]
	s_waitcnt lgkmcnt(10)
	v_mfma_f32_16x16x32_bf16 v[24:27], v[166:169], v[182:185], v[24:27]
	s_waitcnt lgkmcnt(9)
	v_mfma_f32_16x16x32_bf16 v[20:23], v[170:173], v[182:185], v[20:23]
	s_waitcnt lgkmcnt(8)
	v_mfma_f32_16x16x32_bf16 v[16:19], v[174:177], v[182:185], v[16:19]
	s_setprio 0
	ds_read2_b64 v[158:161], v220 offset0:136 offset1:140
	ds_read2_b64 v[166:169], v219 offset0:200 offset1:204
	ds_read2_b64 v[170:173], v218 offset0:168 offset1:172
	ds_read2_b64 v[174:177], v181 offset0:136 offset1:140
	s_setprio 1
	s_waitcnt vmcnt(1) lgkmcnt(11)
	v_mfma_f32_16x16x32_bf16 v[182:185], v[198:201], v[104:107], 0
	s_waitcnt lgkmcnt(9)
	v_mfma_f32_16x16x32_bf16 v[186:189], v[206:209], v[104:107], 0
	s_waitcnt vmcnt(0)
	v_mfma_f32_16x16x32_bf16 v[182:185], v[202:205], v[108:111], v[182:185]
	s_waitcnt lgkmcnt(8)
	v_mfma_f32_16x16x32_bf16 v[186:189], v[210:213], v[108:111], v[186:189]
	s_setprio 0
	s_nop 6
	v_cndmask_b32_e64 v136, v182, v186, s[26:27]
	s_waitcnt lgkmcnt(7)
	v_add_f32_e32 v119, v119, v136
	v_exp_f32_e32 v163, v119
	v_cndmask_b32_e64 v119, v183, v187, s[28:29]
	v_cndmask_b32_e64 v181, v184, v188, s[30:31]
	s_waitcnt lgkmcnt(6)
	v_add_f32_e32 v119, v179, v119
	s_waitcnt lgkmcnt(5)
	v_add_f32_e32 v181, v214, v181
	v_exp_f32_e32 v179, v119
	v_exp_f32_e32 v191, v181
	v_cndmask_b32_e64 v181, v185, v189, s[34:35]
	s_waitcnt lgkmcnt(4)
	v_add_f32_e32 v181, v215, v181
	v_exp_f32_e32 v193, v181
	v_cndmask_b32_e64 v119, v163, 0, s[26:27]
	v_cndmask_b32_e64 v136, 0, v163, s[26:27]
	v_add_f32_e32 v162, 0, v162
	v_add_f32_e32 v163, 0, v163
	v_cndmask_b32_e64 v183, v191, 0, s[30:31]
	v_add_f32_e32 v162, v178, v162
	v_add_f32_e32 v163, v179, v163
	v_cndmask_b32_e64 v185, 0, v191, s[30:31]
	v_add_f32_e32 v162, v190, v162
	v_add_f32_e32 v163, v191, v163
	v_cndmask_b32_e64 v184, v193, 0, s[34:35]
	v_add_f32_e32 v162, v192, v162
	v_add_f32_e32 v163, v193, v163
	v_cndmask_b32_e64 v165, v179, 0, s[28:29]
	v_add_f32_e32 v124, v124, v162
	v_add_f32_e32 v125, v125, v163
	v_cndmask_b32_e64 v181, 0, v179, s[28:29]
	v_cndmask_b32_e64 v186, 0, v193, s[34:35]
	v_cvt_pk_bf16_f32 v182, v119, v165
	v_cvt_pk_bf16_f32 v183, v183, v184
	v_cvt_pk_bf16_f32 v184, v136, v181
	v_cvt_pk_bf16_f32 v185, v185, v186
	s_setprio 1
	s_waitcnt lgkmcnt(0)
	v_mfma_f32_16x16x32_bf16 v[12:15], v[174:177], v[182:185], v[12:15]
	v_mfma_f32_16x16x32_bf16 v[8:11], v[170:173], v[182:185], v[8:11]
	v_mfma_f32_16x16x32_bf16 v[4:7], v[166:169], v[182:185], v[4:7]
	v_mfma_f32_16x16x32_bf16 v[0:3], v[158:161], v[182:185], v[0:3]
	s_setprio 0

.LBB0_412:
	s_add_i32 s68, s60, -2
	s_cmp_ge_u32 s68, s38
	s_cselect_b64 s[72:73], -1, 0
	s_cmp_lt_u32 s68, s39
	s_cselect_b64 vcc, -1, 0
	s_and_b64 s[72:73], s[72:73], vcc
	s_andn2_b64 vcc, exec, s[72:73]
	s_cbranch_vccnz .LBB0_414
	v_add_u32_e32 v178, v150, v149
	v_add_u32_e32 v181, 0x6800, v178
	v_add_u32_e32 v218, 0x7000, v178
	v_add_u32_e32 v219, 0x7800, v178
	v_add_u32_e32 v178, v150, v151
	v_add_u32_e32 v119, v148, v149
	v_add_u32_e32 v136, s70, v152
	v_add_u32_sdwa v163, s70, v143 dst_sel:DWORD dst_unused:UNUSED_PAD src0_sel:DWORD src1_sel:BYTE_2
	v_add_u32_sdwa v165, s70, v143 dst_sel:DWORD dst_unused:UNUSED_PAD src0_sel:DWORD src1_sel:BYTE_3
	v_add_u32_e32 v220, 0x6800, v178
	v_add_u32_sdwa v179, s70, v141 dst_sel:DWORD dst_unused:UNUSED_PAD src0_sel:DWORD src1_sel:BYTE_1
	ds_read_b128 v[158:161], v119 offset:18432
	ds_read_b128 v[166:169], v119 offset:18496
	ds_read_b128 v[170:173], v119 offset:20736
	ds_read_b128 v[174:177], v119 offset:20800
	v_add_u32_e32 v162, s70, v153
	ds_read2_b64 v[182:185], v181 offset0:128 offset1:132
	ds_read2_b64 v[186:189], v218 offset0:160 offset1:164
	ds_read2_b64 v[190:193], v219 offset0:192 offset1:196
	ds_read2_b64 v[194:197], v220 offset0:128 offset1:132
	ds_read_b128 v[198:201], v119 offset:19584
	ds_read_b128 v[202:205], v119 offset:19648
	ds_read_b128 v[206:209], v119 offset:21888
	ds_read_b128 v[210:213], v119 offset:21952
	v_add_u32_e32 v178, s70, v155
	v_add_u32_sdwa v214, s70, v142 dst_sel:DWORD dst_unused:UNUSED_PAD src0_sel:DWORD src1_sel:BYTE_2
	v_add_u32_sdwa v215, s70, v142 dst_sel:DWORD dst_unused:UNUSED_PAD src0_sel:DWORD src1_sel:BYTE_3
	ds_read_b32 v136, v136 offset:41984
	ds_read_b32 v216, v162 offset:41984
	ds_read_b32 v163, v163 offset:41984
	ds_read_b32 v165, v165 offset:41984
	ds_read_b32 v217, v178 offset:41984
	ds_read_b32 v179, v179 offset:41984
	ds_read_b32 v221, v214 offset:41984
	ds_read_b32 v222, v215 offset:41984
	s_setprio 1
	s_waitcnt vmcnt(7) lgkmcnt(14)
	v_mfma_f32_16x16x32_bf16 v[158:161], v[158:161], v[80:83], 0
	s_waitcnt vmcnt(6)
	v_mfma_f32_16x16x32_bf16 v[158:161], v[166:169], v[84:87], v[158:161]
	v_mfma_f32_16x16x32_bf16 v[166:169], v[170:173], v[80:83], 0
	v_mfma_f32_16x16x32_bf16 v[166:169], v[174:177], v[84:87], v[166:169]
	s_setprio 0
	s_nop 6
	v_cndmask_b32_e64 v158, v166, v158, s[20:21]
	s_waitcnt lgkmcnt(7)
	v_add_f32_e32 v136, v136, v158
	v_exp_f32_e32 v162, v136
	v_cndmask_b32_e64 v136, v159, v167, s[10:11]
	v_cndmask_b32_e64 v159, v160, v168, s[12:13]
	s_waitcnt lgkmcnt(5)
	v_add_f32_e32 v159, v163, v159
	v_add_f32_e32 v136, v216, v136
	v_exp_f32_e32 v214, v159
	v_cndmask_b32_e64 v159, v161, v169, s[14:15]
	v_exp_f32_e32 v178, v136
	s_waitcnt lgkmcnt(4)
	v_add_f32_e32 v159, v165, v159
	v_exp_f32_e32 v216, v159
	v_cndmask_b32_e64 v159, v214, 0, s[12:13]
	v_cndmask_b32_e64 v158, v178, 0, s[10:11]
	v_cndmask_b32_e64 v160, 0, v178, s[10:11]
	v_cndmask_b32_e64 v161, 0, v214, s[12:13]
	v_cndmask_b32_e64 v136, 0, v162, s[20:21]
	v_cndmask_b32_e64 v166, v162, 0, s[20:21]
	v_cndmask_b32_e64 v163, v216, 0, s[14:15]
	v_cndmask_b32_e64 v165, 0, v216, s[14:15]
	v_cvt_pk_bf16_f32 v158, v136, v158
	v_cvt_pk_bf16_f32 v159, v159, v163
	v_cvt_pk_bf16_f32 v160, v166, v160
	v_cvt_pk_bf16_f32 v161, v161, v165
	s_setprio 1
	v_mfma_f32_16x16x32_bf16 v[60:63], v[182:185], v[158:161], v[60:63]
	v_mfma_f32_16x16x32_bf16 v[56:59], v[186:189], v[158:161], v[56:59]
	v_mfma_f32_16x16x32_bf16 v[52:55], v[190:193], v[158:161], v[52:55]
	v_mfma_f32_16x16x32_bf16 v[48:51], v[194:197], v[158:161], v[48:51]
	s_setprio 0
	ds_read2_b64 v[158:161], v181 offset0:130 offset1:134
	ds_read2_b64 v[166:169], v218 offset0:162 offset1:166
	ds_read2_b64 v[170:173], v219 offset0:194 offset1:198
	ds_read2_b64 v[174:177], v220 offset0:130 offset1:134
	ds_read_b128 v[182:185], v119 offset:21888
	ds_read_b128 v[186:189], v119 offset:21952
	ds_read_b128 v[190:193], v119 offset:24192
	ds_read_b128 v[194:197], v119 offset:24256
	v_add_u32_e32 v136, s70, v156
	v_add_u32_sdwa v165, s70, v140 dst_sel:DWORD dst_unused:UNUSED_PAD src0_sel:DWORD src1_sel:BYTE_2
	v_add_u32_sdwa v163, s70, v139 dst_sel:DWORD dst_unused:UNUSED_PAD src0_sel:DWORD src1_sel:BYTE_1
	v_add_u32_sdwa v215, s70, v140 dst_sel:DWORD dst_unused:UNUSED_PAD src0_sel:DWORD src1_sel:BYTE_3
	ds_read_b32 v136, v136 offset:41984
	ds_read_b32 v223, v163 offset:41984
	ds_read_b32 v165, v165 offset:41984
	ds_read_b32 v224, v215 offset:41984
	s_setprio 1
	s_waitcnt vmcnt(5)
	v_mfma_f32_16x16x32_bf16 v[198:201], v[198:201], v[88:91], 0
	s_waitcnt vmcnt(4)
	v_mfma_f32_16x16x32_bf16 v[198:201], v[202:205], v[92:95], v[198:201]
	v_mfma_f32_16x16x32_bf16 v[202:205], v[206:209], v[88:91], 0
	v_mfma_f32_16x16x32_bf16 v[202:205], v[210:213], v[92:95], v[202:205]
	s_setprio 0
	s_nop 6
	v_cndmask_b32_e64 v163, v198, v202, s[16:17]
	s_waitcnt lgkmcnt(14)
	v_add_f32_e32 v163, v217, v163
	v_cndmask_b32_e64 v198, v199, v203, s[18:19]
	v_cndmask_b32_e64 v200, v200, v204, s[6:7]
	v_exp_f32_e32 v163, v163
	v_add_f32_e32 v179, v179, v198
	s_waitcnt lgkmcnt(13)
	v_add_f32_e32 v200, v221, v200
	v_exp_f32_e32 v179, v179
	v_exp_f32_e32 v215, v200
	v_cndmask_b32_e64 v200, v201, v205, s[8:9]
	s_waitcnt lgkmcnt(12)
	v_add_f32_e32 v200, v222, v200
	v_exp_f32_e32 v217, v200
	v_cndmask_b32_e64 v198, v163, 0, s[16:17]
	v_cndmask_b32_e64 v202, 0, v163, s[16:17]
	v_add_f32_e32 v162, 0, v162
	v_add_f32_e32 v163, 0, v163
	v_cndmask_b32_e64 v199, v179, 0, s[18:19]
	v_add_f32_e32 v162, v178, v162
	v_add_f32_e32 v163, v179, v163
	v_cndmask_b32_e64 v200, 0, v179, s[18:19]
	v_add_f32_e32 v162, v214, v162
	v_add_f32_e32 v163, v215, v163
	v_cndmask_b32_e64 v201, v215, 0, s[6:7]
	v_add_f32_e32 v162, v216, v162
	v_add_f32_e32 v163, v217, v163
	v_cndmask_b32_e64 v203, 0, v215, s[6:7]
	v_add_f32_e32 v130, v130, v162
	v_add_f32_e32 v131, v131, v163
	v_cndmask_b32_e64 v204, v217, 0, s[8:9]
	v_cndmask_b32_e64 v205, 0, v217, s[8:9]
	v_cvt_pk_bf16_f32 v198, v198, v199
	v_cvt_pk_bf16_f32 v199, v201, v204
	v_cvt_pk_bf16_f32 v200, v202, v200
	v_cvt_pk_bf16_f32 v201, v203, v205
	s_setprio 1
	s_waitcnt lgkmcnt(11)
	v_mfma_f32_16x16x32_bf16 v[44:47], v[158:161], v[198:201], v[44:47]
	s_waitcnt lgkmcnt(10)
	v_mfma_f32_16x16x32_bf16 v[40:43], v[166:169], v[198:201], v[40:43]
	s_waitcnt lgkmcnt(9)
	v_mfma_f32_16x16x32_bf16 v[36:39], v[170:173], v[198:201], v[36:39]
	s_waitcnt lgkmcnt(8)
	v_mfma_f32_16x16x32_bf16 v[32:35], v[174:177], v[198:201], v[32:35]
	s_setprio 0
	ds_read2_b64 v[158:161], v181 offset0:134 offset1:138
	ds_read2_b64 v[166:169], v218 offset0:166 offset1:170
	ds_read2_b64 v[170:173], v219 offset0:198 offset1:202
	ds_read2_b64 v[174:177], v220 offset0:134 offset1:138
	ds_read_b128 v[198:201], v119 offset:23040
	ds_read_b128 v[202:205], v119 offset:23104
	v_add_u32_e32 v119, v148, v151
	ds_read_b128 v[206:209], v119 offset:18432
	ds_read_b128 v[210:213], v119 offset:18496
	v_add_u32_e32 v119, s70, v154
	v_add_u32_sdwa v162, s70, v144 dst_sel:DWORD dst_unused:UNUSED_PAD src0_sel:DWORD src1_sel:BYTE_1
	v_add_u32_sdwa v163, s70, v145 dst_sel:DWORD dst_unused:UNUSED_PAD src0_sel:DWORD src1_sel:BYTE_2
	v_add_u32_sdwa v178, s70, v145 dst_sel:DWORD dst_unused:UNUSED_PAD src0_sel:DWORD src1_sel:BYTE_3
	ds_read_b32 v119, v119 offset:41984
	ds_read_b32 v179, v162 offset:41984
	ds_read_b32 v214, v163 offset:41984
	ds_read_b32 v215, v178 offset:41984
	s_setprio 1
	s_waitcnt vmcnt(3) lgkmcnt(14)
	v_mfma_f32_16x16x32_bf16 v[182:185], v[182:185], v[96:99], 0
	s_waitcnt vmcnt(2)
	v_mfma_f32_16x16x32_bf16 v[182:185], v[186:189], v[100:103], v[182:185]
	v_mfma_f32_16x16x32_bf16 v[186:189], v[190:193], v[96:99], 0
	v_mfma_f32_16x16x32_bf16 v[186:189], v[194:197], v[100:103], v[186:189]
	s_setprio 0
	s_nop 6
	v_cndmask_b32_e64 v162, v186, v182, s[2:3]
	v_add_f32_e32 v136, v136, v162
	v_exp_f32_e32 v162, v136
	v_cndmask_b32_e64 v136, v187, v183, s[4:5]
	v_cndmask_b32_e64 v183, v184, v188, s[22:23]
	s_waitcnt lgkmcnt(13)
	v_add_f32_e32 v165, v165, v183
	v_exp_f32_e32 v190, v165
	v_cndmask_b32_e64 v165, v185, v189, s[24:25]
	v_add_f32_e32 v136, v223, v136
	s_waitcnt lgkmcnt(12)
	v_add_f32_e32 v165, v224, v165
	v_exp_f32_e32 v178, v136
	v_exp_f32_e32 v192, v165
	v_cndmask_b32_e64 v183, v190, 0, s[22:23]
	v_cndmask_b32_e64 v185, 0, v190, s[22:23]
	v_cndmask_b32_e64 v182, 0, v178, s[4:5]
	v_cndmask_b32_e64 v184, v192, 0, s[24:25]
	v_cndmask_b32_e64 v136, 0, v162, s[2:3]
	v_cndmask_b32_e64 v163, v162, 0, s[2:3]
	v_cndmask_b32_e64 v165, v178, 0, s[4:5]
	v_cndmask_b32_e64 v186, 0, v192, s[24:25]
	v_cvt_pk_bf16_f32 v182, v136, v182
	v_cvt_pk_bf16_f32 v183, v183, v184
	v_cvt_pk_bf16_f32 v184, v163, v165
	v_cvt_pk_bf16_f32 v185, v185, v186
	s_setprio 1
	s_waitcnt lgkmcnt(11)
	v_mfma_f32_16x16x32_bf16 v[28:31], v[158:161], v[182:185], v[28:31]
	s_waitcnt lgkmcnt(10)
	v_mfma_f32_16x16x32_bf16 v[24:27], v[166:169], v[182:185], v[24:27]
	s_waitcnt lgkmcnt(9)
	v_mfma_f32_16x16x32_bf16 v[20:23], v[170:173], v[182:185], v[20:23]
	s_waitcnt lgkmcnt(8)
	v_mfma_f32_16x16x32_bf16 v[16:19], v[174:177], v[182:185], v[16:19]
	s_setprio 0
	ds_read2_b64 v[158:161], v220 offset0:136 offset1:140
	ds_read2_b64 v[166:169], v219 offset0:200 offset1:204
	ds_read2_b64 v[170:173], v218 offset0:168 offset1:172
	ds_read2_b64 v[174:177], v181 offset0:136 offset1:140
	s_setprio 1
	s_waitcnt vmcnt(1) lgkmcnt(11)
	v_mfma_f32_16x16x32_bf16 v[182:185], v[198:201], v[104:107], 0
	s_waitcnt lgkmcnt(9)
	v_mfma_f32_16x16x32_bf16 v[186:189], v[206:209], v[104:107], 0
	s_waitcnt vmcnt(0)
	v_mfma_f32_16x16x32_bf16 v[182:185], v[202:205], v[108:111], v[182:185]
	s_waitcnt lgkmcnt(8)
	v_mfma_f32_16x16x32_bf16 v[186:189], v[210:213], v[108:111], v[186:189]
	s_setprio 0
	s_nop 6
	v_cndmask_b32_e64 v136, v182, v186, s[26:27]
	s_waitcnt lgkmcnt(7)
	v_add_f32_e32 v119, v119, v136
	v_exp_f32_e32 v163, v119
	v_cndmask_b32_e64 v119, v183, v187, s[28:29]
	v_cndmask_b32_e64 v181, v184, v188, s[30:31]
	s_waitcnt lgkmcnt(6)
	v_add_f32_e32 v119, v179, v119
	s_waitcnt lgkmcnt(5)
	v_add_f32_e32 v181, v214, v181
	v_exp_f32_e32 v179, v119
	v_exp_f32_e32 v191, v181
	v_cndmask_b32_e64 v181, v185, v189, s[34:35]
	s_waitcnt lgkmcnt(4)
	v_add_f32_e32 v181, v215, v181
	v_exp_f32_e32 v193, v181
	v_cndmask_b32_e64 v119, v163, 0, s[26:27]
	v_cndmask_b32_e64 v136, 0, v163, s[26:27]
	v_add_f32_e32 v162, 0, v162
	v_add_f32_e32 v163, 0, v163
	v_cndmask_b32_e64 v183, v191, 0, s[30:31]
	v_add_f32_e32 v162, v178, v162
	v_add_f32_e32 v163, v179, v163
	v_cndmask_b32_e64 v185, 0, v191, s[30:31]
	v_add_f32_e32 v162, v190, v162
	v_add_f32_e32 v163, v191, v163
	v_cndmask_b32_e64 v184, v193, 0, s[34:35]
	v_add_f32_e32 v162, v192, v162
	v_add_f32_e32 v163, v193, v163
	v_cndmask_b32_e64 v165, v179, 0, s[28:29]
	v_add_f32_e32 v124, v124, v162
	v_add_f32_e32 v125, v125, v163
	v_cndmask_b32_e64 v181, 0, v179, s[28:29]
	v_cndmask_b32_e64 v186, 0, v193, s[34:35]
	v_cvt_pk_bf16_f32 v182, v119, v165
	v_cvt_pk_bf16_f32 v183, v183, v184
	v_cvt_pk_bf16_f32 v184, v136, v181
	v_cvt_pk_bf16_f32 v185, v185, v186
	s_setprio 1
	s_waitcnt lgkmcnt(0)
	v_mfma_f32_16x16x32_bf16 v[12:15], v[174:177], v[182:185], v[12:15]
	v_mfma_f32_16x16x32_bf16 v[8:11], v[170:173], v[182:185], v[8:11]
	v_mfma_f32_16x16x32_bf16 v[4:7], v[166:169], v[182:185], v[4:7]
	v_mfma_f32_16x16x32_bf16 v[0:3], v[158:161], v[182:185], v[0:3]
	s_setprio 0

.LBB0_489:
	s_add_i32 s68, s48, -3
	s_cmp_ge_u32 s68, s38
	s_cselect_b64 s[64:65], -1, 0
	s_cmp_lt_u32 s68, s39
	s_cselect_b64 s[94:95], -1, 0
	s_and_b64 s[64:65], s[64:65], s[94:95]
	s_andn2_b64 vcc, exec, s[64:65]
	s_cbranch_vccnz .LBB0_491
	v_add_u32_e32 v178, v150, v149
	v_add_u32_e32 v181, 0x2000, v178
	v_add_u32_e32 v218, 0x2800, v178
	v_add_u32_e32 v219, 0x3000, v178
	v_add_u32_e32 v178, v150, v151
	v_add_u32_e32 v119, v148, v149
	v_add_u32_e32 v136, s66, v152
	v_add_u32_sdwa v163, s66, v143 dst_sel:DWORD dst_unused:UNUSED_PAD src0_sel:DWORD src1_sel:BYTE_2
	v_add_u32_sdwa v165, s66, v143 dst_sel:DWORD dst_unused:UNUSED_PAD src0_sel:DWORD src1_sel:BYTE_3
	v_add_u32_e32 v220, 0x2000, v178
	v_add_u32_sdwa v179, s66, v141 dst_sel:DWORD dst_unused:UNUSED_PAD src0_sel:DWORD src1_sel:BYTE_1
	ds_read_b128 v[158:161], v119
	ds_read_b128 v[166:169], v119 offset:64
	ds_read_b128 v[170:173], v119 offset:2304
	ds_read_b128 v[174:177], v119 offset:2368
	v_add_u32_e32 v162, s66, v153
	ds_read2_b64 v[182:185], v181 offset0:128 offset1:132
	ds_read2_b64 v[186:189], v218 offset0:160 offset1:164
	ds_read2_b64 v[190:193], v219 offset0:192 offset1:196
	ds_read2_b64 v[194:197], v220 offset0:128 offset1:132
	ds_read_b128 v[198:201], v119 offset:1152
	ds_read_b128 v[202:205], v119 offset:1216
	ds_read_b128 v[206:209], v119 offset:3456
	ds_read_b128 v[210:213], v119 offset:3520
	v_add_u32_e32 v178, s66, v155
	v_add_u32_sdwa v214, s66, v142 dst_sel:DWORD dst_unused:UNUSED_PAD src0_sel:DWORD src1_sel:BYTE_2
	v_add_u32_sdwa v215, s66, v142 dst_sel:DWORD dst_unused:UNUSED_PAD src0_sel:DWORD src1_sel:BYTE_3
	ds_read_b32 v136, v136 offset:41856
	ds_read_b32 v216, v162 offset:41856
	ds_read_b32 v163, v163 offset:41856
	ds_read_b32 v165, v165 offset:41856
	ds_read_b32 v217, v178 offset:41856
	ds_read_b32 v179, v179 offset:41856
	ds_read_b32 v221, v214 offset:41856
	ds_read_b32 v222, v215 offset:41856
	s_setprio 1
	s_waitcnt vmcnt(7) lgkmcnt(14)
	v_mfma_f32_16x16x32_bf16 v[158:161], v[158:161], v[80:83], 0
	s_waitcnt vmcnt(6)
	v_mfma_f32_16x16x32_bf16 v[158:161], v[166:169], v[84:87], v[158:161]
	v_mfma_f32_16x16x32_bf16 v[166:169], v[170:173], v[80:83], 0
	v_mfma_f32_16x16x32_bf16 v[166:169], v[174:177], v[84:87], v[166:169]
	s_setprio 0
	s_nop 6
	v_cndmask_b32_e64 v158, v166, v158, s[20:21]
	s_waitcnt lgkmcnt(7)
	v_add_f32_e32 v136, v136, v158
	v_exp_f32_e32 v162, v136
	v_cndmask_b32_e64 v136, v159, v167, s[10:11]
	v_cndmask_b32_e64 v159, v160, v168, s[12:13]
	s_waitcnt lgkmcnt(5)
	v_add_f32_e32 v159, v163, v159
	v_add_f32_e32 v136, v216, v136
	v_exp_f32_e32 v214, v159
	v_cndmask_b32_e64 v159, v161, v169, s[14:15]
	v_exp_f32_e32 v178, v136
	s_waitcnt lgkmcnt(4)
	v_add_f32_e32 v159, v165, v159
	v_exp_f32_e32 v216, v159
	v_cndmask_b32_e64 v159, v214, 0, s[12:13]
	v_cndmask_b32_e64 v158, v178, 0, s[10:11]
	v_cndmask_b32_e64 v160, 0, v178, s[10:11]
	v_cndmask_b32_e64 v161, 0, v214, s[12:13]
	v_cndmask_b32_e64 v136, 0, v162, s[20:21]
	v_cndmask_b32_e64 v166, v162, 0, s[20:21]
	v_cndmask_b32_e64 v163, v216, 0, s[14:15]
	v_cndmask_b32_e64 v165, 0, v216, s[14:15]
	v_cvt_pk_bf16_f32 v158, v136, v158
	v_cvt_pk_bf16_f32 v159, v159, v163
	v_cvt_pk_bf16_f32 v160, v166, v160
	v_cvt_pk_bf16_f32 v161, v161, v165
	s_setprio 1
	v_mfma_f32_16x16x32_bf16 v[60:63], v[182:185], v[158:161], v[60:63]
	v_mfma_f32_16x16x32_bf16 v[56:59], v[186:189], v[158:161], v[56:59]
	v_mfma_f32_16x16x32_bf16 v[52:55], v[190:193], v[158:161], v[52:55]
	v_mfma_f32_16x16x32_bf16 v[48:51], v[194:197], v[158:161], v[48:51]
	s_setprio 0
	ds_read2_b64 v[158:161], v181 offset0:130 offset1:134
	ds_read2_b64 v[166:169], v218 offset0:162 offset1:166
	ds_read2_b64 v[170:173], v219 offset0:194 offset1:198
	ds_read2_b64 v[174:177], v220 offset0:130 offset1:134
	ds_read_b128 v[182:185], v119 offset:3456
	ds_read_b128 v[186:189], v119 offset:3520
	ds_read_b128 v[190:193], v119 offset:5760
	ds_read_b128 v[194:197], v119 offset:5824
	v_add_u32_e32 v136, s66, v156
	v_add_u32_sdwa v165, s66, v140 dst_sel:DWORD dst_unused:UNUSED_PAD src0_sel:DWORD src1_sel:BYTE_2
	v_add_u32_sdwa v163, s66, v139 dst_sel:DWORD dst_unused:UNUSED_PAD src0_sel:DWORD src1_sel:BYTE_1
	v_add_u32_sdwa v215, s66, v140 dst_sel:DWORD dst_unused:UNUSED_PAD src0_sel:DWORD src1_sel:BYTE_3
	ds_read_b32 v136, v136 offset:41856
	ds_read_b32 v223, v163 offset:41856
	ds_read_b32 v165, v165 offset:41856
	ds_read_b32 v224, v215 offset:41856
	s_setprio 1
	s_waitcnt vmcnt(5)
	v_mfma_f32_16x16x32_bf16 v[198:201], v[198:201], v[88:91], 0
	s_waitcnt vmcnt(4)
	v_mfma_f32_16x16x32_bf16 v[198:201], v[202:205], v[92:95], v[198:201]
	v_mfma_f32_16x16x32_bf16 v[202:205], v[206:209], v[88:91], 0
	v_mfma_f32_16x16x32_bf16 v[202:205], v[210:213], v[92:95], v[202:205]
	s_setprio 0
	s_nop 6
	v_cndmask_b32_e64 v163, v198, v202, s[16:17]
	s_waitcnt lgkmcnt(14)
	v_add_f32_e32 v163, v217, v163
	v_cndmask_b32_e64 v198, v199, v203, s[18:19]
	v_cndmask_b32_e64 v200, v200, v204, s[6:7]
	v_exp_f32_e32 v163, v163
	v_add_f32_e32 v179, v179, v198
	s_waitcnt lgkmcnt(13)
	v_add_f32_e32 v200, v221, v200
	v_exp_f32_e32 v179, v179
	v_exp_f32_e32 v215, v200
	v_cndmask_b32_e64 v200, v201, v205, s[8:9]
	s_waitcnt lgkmcnt(12)
	v_add_f32_e32 v200, v222, v200
	v_exp_f32_e32 v217, v200
	v_cndmask_b32_e64 v198, v163, 0, s[16:17]
	v_cndmask_b32_e64 v202, 0, v163, s[16:17]
	v_add_f32_e32 v162, 0, v162
	v_add_f32_e32 v163, 0, v163
	v_cndmask_b32_e64 v199, v179, 0, s[18:19]
	v_add_f32_e32 v162, v178, v162
	v_add_f32_e32 v163, v179, v163
	v_cndmask_b32_e64 v200, 0, v179, s[18:19]
	v_add_f32_e32 v162, v214, v162
	v_add_f32_e32 v163, v215, v163
	v_cndmask_b32_e64 v201, v215, 0, s[6:7]
	v_add_f32_e32 v162, v216, v162
	v_add_f32_e32 v163, v217, v163
	v_cndmask_b32_e64 v203, 0, v215, s[6:7]
	v_add_f32_e32 v130, v130, v162
	v_add_f32_e32 v131, v131, v163
	v_cndmask_b32_e64 v204, v217, 0, s[8:9]
	v_cndmask_b32_e64 v205, 0, v217, s[8:9]
	v_cvt_pk_bf16_f32 v198, v198, v199
	v_cvt_pk_bf16_f32 v199, v201, v204
	v_cvt_pk_bf16_f32 v200, v202, v200
	v_cvt_pk_bf16_f32 v201, v203, v205
	s_setprio 1
	s_waitcnt lgkmcnt(11)
	v_mfma_f32_16x16x32_bf16 v[44:47], v[158:161], v[198:201], v[44:47]
	s_waitcnt lgkmcnt(10)
	v_mfma_f32_16x16x32_bf16 v[40:43], v[166:169], v[198:201], v[40:43]
	s_waitcnt lgkmcnt(9)
	v_mfma_f32_16x16x32_bf16 v[36:39], v[170:173], v[198:201], v[36:39]
	s_waitcnt lgkmcnt(8)
	v_mfma_f32_16x16x32_bf16 v[32:35], v[174:177], v[198:201], v[32:35]
	s_setprio 0
	ds_read2_b64 v[158:161], v181 offset0:134 offset1:138
	ds_read2_b64 v[166:169], v218 offset0:166 offset1:170
	ds_read2_b64 v[170:173], v219 offset0:198 offset1:202
	ds_read2_b64 v[174:177], v220 offset0:134 offset1:138
	ds_read_b128 v[198:201], v119 offset:4608
	ds_read_b128 v[202:205], v119 offset:4672
	v_add_u32_e32 v119, v148, v151
	ds_read_b128 v[206:209], v119
	ds_read_b128 v[210:213], v119 offset:64
	v_add_u32_e32 v119, s66, v154
	v_add_u32_sdwa v162, s66, v144 dst_sel:DWORD dst_unused:UNUSED_PAD src0_sel:DWORD src1_sel:BYTE_1
	v_add_u32_sdwa v163, s66, v145 dst_sel:DWORD dst_unused:UNUSED_PAD src0_sel:DWORD src1_sel:BYTE_2
	v_add_u32_sdwa v178, s66, v145 dst_sel:DWORD dst_unused:UNUSED_PAD src0_sel:DWORD src1_sel:BYTE_3
	ds_read_b32 v119, v119 offset:41856
	ds_read_b32 v179, v162 offset:41856
	ds_read_b32 v214, v163 offset:41856
	ds_read_b32 v215, v178 offset:41856
	s_setprio 1
	s_waitcnt vmcnt(3) lgkmcnt(14)
	v_mfma_f32_16x16x32_bf16 v[182:185], v[182:185], v[96:99], 0
	s_waitcnt vmcnt(2)
	v_mfma_f32_16x16x32_bf16 v[182:185], v[186:189], v[100:103], v[182:185]
	v_mfma_f32_16x16x32_bf16 v[186:189], v[190:193], v[96:99], 0
	v_mfma_f32_16x16x32_bf16 v[186:189], v[194:197], v[100:103], v[186:189]
	s_setprio 0
	s_nop 6
	v_cndmask_b32_e64 v162, v186, v182, s[2:3]
	v_add_f32_e32 v136, v136, v162
	v_exp_f32_e32 v162, v136
	v_cndmask_b32_e64 v136, v187, v183, s[4:5]
	v_cndmask_b32_e64 v183, v184, v188, s[22:23]
	s_waitcnt lgkmcnt(13)
	v_add_f32_e32 v165, v165, v183
	v_exp_f32_e32 v190, v165
	v_cndmask_b32_e64 v165, v185, v189, s[24:25]
	v_add_f32_e32 v136, v223, v136
	s_waitcnt lgkmcnt(12)
	v_add_f32_e32 v165, v224, v165
	v_exp_f32_e32 v178, v136
	v_exp_f32_e32 v192, v165
	v_cndmask_b32_e64 v183, v190, 0, s[22:23]
	v_cndmask_b32_e64 v185, 0, v190, s[22:23]
	v_cndmask_b32_e64 v182, 0, v178, s[4:5]
	v_cndmask_b32_e64 v184, v192, 0, s[24:25]
	v_cndmask_b32_e64 v136, 0, v162, s[2:3]
	v_cndmask_b32_e64 v163, v162, 0, s[2:3]
	v_cndmask_b32_e64 v165, v178, 0, s[4:5]
	v_cndmask_b32_e64 v186, 0, v192, s[24:25]
	v_cvt_pk_bf16_f32 v182, v136, v182
	v_cvt_pk_bf16_f32 v183, v183, v184
	v_cvt_pk_bf16_f32 v184, v163, v165
	v_cvt_pk_bf16_f32 v185, v185, v186
	s_setprio 1
	s_waitcnt lgkmcnt(11)
	v_mfma_f32_16x16x32_bf16 v[28:31], v[158:161], v[182:185], v[28:31]
	s_waitcnt lgkmcnt(10)
	v_mfma_f32_16x16x32_bf16 v[24:27], v[166:169], v[182:185], v[24:27]
	s_waitcnt lgkmcnt(9)
	v_mfma_f32_16x16x32_bf16 v[20:23], v[170:173], v[182:185], v[20:23]
	s_waitcnt lgkmcnt(8)
	v_mfma_f32_16x16x32_bf16 v[16:19], v[174:177], v[182:185], v[16:19]
	s_setprio 0
	ds_read2_b64 v[158:161], v220 offset0:136 offset1:140
	ds_read2_b64 v[166:169], v219 offset0:200 offset1:204
	ds_read2_b64 v[170:173], v218 offset0:168 offset1:172
	ds_read2_b64 v[174:177], v181 offset0:136 offset1:140
	s_setprio 1
	s_waitcnt vmcnt(1) lgkmcnt(11)
	v_mfma_f32_16x16x32_bf16 v[182:185], v[198:201], v[104:107], 0
	s_waitcnt lgkmcnt(9)
	v_mfma_f32_16x16x32_bf16 v[186:189], v[206:209], v[104:107], 0
	s_waitcnt vmcnt(0)
	v_mfma_f32_16x16x32_bf16 v[182:185], v[202:205], v[108:111], v[182:185]
	s_waitcnt lgkmcnt(8)
	v_mfma_f32_16x16x32_bf16 v[186:189], v[210:213], v[108:111], v[186:189]
	s_setprio 0
	s_nop 6
	v_cndmask_b32_e64 v136, v182, v186, s[26:27]
	s_waitcnt lgkmcnt(7)
	v_add_f32_e32 v119, v119, v136
	v_exp_f32_e32 v163, v119
	v_cndmask_b32_e64 v119, v183, v187, s[28:29]
	v_cndmask_b32_e64 v181, v184, v188, s[30:31]
	s_waitcnt lgkmcnt(6)
	v_add_f32_e32 v119, v179, v119
	s_waitcnt lgkmcnt(5)
	v_add_f32_e32 v181, v214, v181
	v_exp_f32_e32 v179, v119
	v_exp_f32_e32 v191, v181
	v_cndmask_b32_e64 v181, v185, v189, s[34:35]
	s_waitcnt lgkmcnt(4)
	v_add_f32_e32 v181, v215, v181
	v_exp_f32_e32 v193, v181
	v_cndmask_b32_e64 v119, v163, 0, s[26:27]
	v_cndmask_b32_e64 v136, 0, v163, s[26:27]
	v_add_f32_e32 v162, 0, v162
	v_add_f32_e32 v163, 0, v163
	v_cndmask_b32_e64 v183, v191, 0, s[30:31]
	v_add_f32_e32 v162, v178, v162
	v_add_f32_e32 v163, v179, v163
	v_cndmask_b32_e64 v185, 0, v191, s[30:31]
	v_add_f32_e32 v162, v190, v162
	v_add_f32_e32 v163, v191, v163
	v_cndmask_b32_e64 v184, v193, 0, s[34:35]
	v_add_f32_e32 v162, v192, v162
	v_add_f32_e32 v163, v193, v163
	v_cndmask_b32_e64 v165, v179, 0, s[28:29]
	v_add_f32_e32 v124, v124, v162
	v_add_f32_e32 v125, v125, v163
	v_cndmask_b32_e64 v181, 0, v179, s[28:29]
	v_cndmask_b32_e64 v186, 0, v193, s[34:35]
	v_cvt_pk_bf16_f32 v182, v119, v165
	v_cvt_pk_bf16_f32 v183, v183, v184
	v_cvt_pk_bf16_f32 v184, v136, v181
	v_cvt_pk_bf16_f32 v185, v185, v186
	s_setprio 1
	s_waitcnt lgkmcnt(0)
	v_mfma_f32_16x16x32_bf16 v[12:15], v[174:177], v[182:185], v[12:15]
	v_mfma_f32_16x16x32_bf16 v[8:11], v[170:173], v[182:185], v[8:11]
	v_mfma_f32_16x16x32_bf16 v[4:7], v[166:169], v[182:185], v[4:7]
	v_mfma_f32_16x16x32_bf16 v[0:3], v[158:161], v[182:185], v[0:3]
	s_setprio 0

.LBB0_496:
	s_add_i32 s64, s48, -2
	s_cmp_ge_u32 s64, s38
	s_cselect_b64 s[68:69], -1, 0
	s_cmp_lt_u32 s64, s39
	s_cselect_b64 s[94:95], -1, 0
	s_and_b64 s[68:69], s[68:69], s[94:95]
	s_andn2_b64 vcc, exec, s[68:69]
	s_cbranch_vccnz .LBB0_498
	v_add_u32_e32 v178, v150, v149
	v_add_u32_e32 v181, 0x6800, v178
	v_add_u32_e32 v218, 0x7000, v178
	v_add_u32_e32 v219, 0x7800, v178
	v_add_u32_e32 v178, v150, v151
	v_add_u32_e32 v119, v148, v149
	v_add_u32_e32 v136, s66, v152
	v_add_u32_sdwa v163, s66, v143 dst_sel:DWORD dst_unused:UNUSED_PAD src0_sel:DWORD src1_sel:BYTE_2
	v_add_u32_sdwa v165, s66, v143 dst_sel:DWORD dst_unused:UNUSED_PAD src0_sel:DWORD src1_sel:BYTE_3
	v_add_u32_e32 v220, 0x6800, v178
	v_add_u32_sdwa v179, s66, v141 dst_sel:DWORD dst_unused:UNUSED_PAD src0_sel:DWORD src1_sel:BYTE_1
	ds_read_b128 v[158:161], v119 offset:18432
	ds_read_b128 v[166:169], v119 offset:18496
	ds_read_b128 v[170:173], v119 offset:20736
	ds_read_b128 v[174:177], v119 offset:20800
	v_add_u32_e32 v162, s66, v153
	ds_read2_b64 v[182:185], v181 offset0:128 offset1:132
	ds_read2_b64 v[186:189], v218 offset0:160 offset1:164
	ds_read2_b64 v[190:193], v219 offset0:192 offset1:196
	ds_read2_b64 v[194:197], v220 offset0:128 offset1:132
	ds_read_b128 v[198:201], v119 offset:19584
	ds_read_b128 v[202:205], v119 offset:19648
	ds_read_b128 v[206:209], v119 offset:21888
	ds_read_b128 v[210:213], v119 offset:21952
	v_add_u32_e32 v178, s66, v155
	v_add_u32_sdwa v214, s66, v142 dst_sel:DWORD dst_unused:UNUSED_PAD src0_sel:DWORD src1_sel:BYTE_2
	v_add_u32_sdwa v215, s66, v142 dst_sel:DWORD dst_unused:UNUSED_PAD src0_sel:DWORD src1_sel:BYTE_3
	ds_read_b32 v136, v136 offset:41984
	ds_read_b32 v216, v162 offset:41984
	ds_read_b32 v163, v163 offset:41984
	ds_read_b32 v165, v165 offset:41984
	ds_read_b32 v217, v178 offset:41984
	ds_read_b32 v179, v179 offset:41984
	ds_read_b32 v221, v214 offset:41984
	ds_read_b32 v222, v215 offset:41984
	s_setprio 1
	s_waitcnt vmcnt(7) lgkmcnt(14)
	v_mfma_f32_16x16x32_bf16 v[158:161], v[158:161], v[80:83], 0
	s_waitcnt vmcnt(6)
	v_mfma_f32_16x16x32_bf16 v[158:161], v[166:169], v[84:87], v[158:161]
	v_mfma_f32_16x16x32_bf16 v[166:169], v[170:173], v[80:83], 0
	v_mfma_f32_16x16x32_bf16 v[166:169], v[174:177], v[84:87], v[166:169]
	s_setprio 0
	s_nop 6
	v_cndmask_b32_e64 v158, v166, v158, s[20:21]
	s_waitcnt lgkmcnt(7)
	v_add_f32_e32 v136, v136, v158
	v_exp_f32_e32 v162, v136
	v_cndmask_b32_e64 v136, v159, v167, s[10:11]
	v_cndmask_b32_e64 v159, v160, v168, s[12:13]
	s_waitcnt lgkmcnt(5)
	v_add_f32_e32 v159, v163, v159
	v_add_f32_e32 v136, v216, v136
	v_exp_f32_e32 v214, v159
	v_cndmask_b32_e64 v159, v161, v169, s[14:15]
	v_exp_f32_e32 v178, v136
	s_waitcnt lgkmcnt(4)
	v_add_f32_e32 v159, v165, v159
	v_exp_f32_e32 v216, v159
	v_cndmask_b32_e64 v159, v214, 0, s[12:13]
	v_cndmask_b32_e64 v158, v178, 0, s[10:11]
	v_cndmask_b32_e64 v160, 0, v178, s[10:11]
	v_cndmask_b32_e64 v161, 0, v214, s[12:13]
	v_cndmask_b32_e64 v136, 0, v162, s[20:21]
	v_cndmask_b32_e64 v166, v162, 0, s[20:21]
	v_cndmask_b32_e64 v163, v216, 0, s[14:15]
	v_cndmask_b32_e64 v165, 0, v216, s[14:15]
	v_cvt_pk_bf16_f32 v158, v136, v158
	v_cvt_pk_bf16_f32 v159, v159, v163
	v_cvt_pk_bf16_f32 v160, v166, v160
	v_cvt_pk_bf16_f32 v161, v161, v165
	s_setprio 1
	v_mfma_f32_16x16x32_bf16 v[60:63], v[182:185], v[158:161], v[60:63]
	v_mfma_f32_16x16x32_bf16 v[56:59], v[186:189], v[158:161], v[56:59]
	v_mfma_f32_16x16x32_bf16 v[52:55], v[190:193], v[158:161], v[52:55]
	v_mfma_f32_16x16x32_bf16 v[48:51], v[194:197], v[158:161], v[48:51]
	s_setprio 0
	ds_read2_b64 v[158:161], v181 offset0:130 offset1:134
	ds_read2_b64 v[166:169], v218 offset0:162 offset1:166
	ds_read2_b64 v[170:173], v219 offset0:194 offset1:198
	ds_read2_b64 v[174:177], v220 offset0:130 offset1:134
	ds_read_b128 v[182:185], v119 offset:21888
	ds_read_b128 v[186:189], v119 offset:21952
	ds_read_b128 v[190:193], v119 offset:24192
	ds_read_b128 v[194:197], v119 offset:24256
	v_add_u32_e32 v136, s66, v156
	v_add_u32_sdwa v165, s66, v140 dst_sel:DWORD dst_unused:UNUSED_PAD src0_sel:DWORD src1_sel:BYTE_2
	v_add_u32_sdwa v163, s66, v139 dst_sel:DWORD dst_unused:UNUSED_PAD src0_sel:DWORD src1_sel:BYTE_1
	v_add_u32_sdwa v215, s66, v140 dst_sel:DWORD dst_unused:UNUSED_PAD src0_sel:DWORD src1_sel:BYTE_3
	ds_read_b32 v136, v136 offset:41984
	ds_read_b32 v223, v163 offset:41984
	ds_read_b32 v165, v165 offset:41984
	ds_read_b32 v224, v215 offset:41984
	s_setprio 1
	s_waitcnt vmcnt(5)
	v_mfma_f32_16x16x32_bf16 v[198:201], v[198:201], v[88:91], 0
	s_waitcnt vmcnt(4)
	v_mfma_f32_16x16x32_bf16 v[198:201], v[202:205], v[92:95], v[198:201]
	v_mfma_f32_16x16x32_bf16 v[202:205], v[206:209], v[88:91], 0
	v_mfma_f32_16x16x32_bf16 v[202:205], v[210:213], v[92:95], v[202:205]
	s_setprio 0
	s_nop 6
	v_cndmask_b32_e64 v163, v198, v202, s[16:17]
	s_waitcnt lgkmcnt(14)
	v_add_f32_e32 v163, v217, v163
	v_cndmask_b32_e64 v198, v199, v203, s[18:19]
	v_cndmask_b32_e64 v200, v200, v204, s[6:7]
	v_exp_f32_e32 v163, v163
	v_add_f32_e32 v179, v179, v198
	s_waitcnt lgkmcnt(13)
	v_add_f32_e32 v200, v221, v200
	v_exp_f32_e32 v179, v179
	v_exp_f32_e32 v215, v200
	v_cndmask_b32_e64 v200, v201, v205, s[8:9]
	s_waitcnt lgkmcnt(12)
	v_add_f32_e32 v200, v222, v200
	v_exp_f32_e32 v217, v200
	v_cndmask_b32_e64 v198, v163, 0, s[16:17]
	v_cndmask_b32_e64 v202, 0, v163, s[16:17]
	v_add_f32_e32 v162, 0, v162
	v_add_f32_e32 v163, 0, v163
	v_cndmask_b32_e64 v199, v179, 0, s[18:19]
	v_add_f32_e32 v162, v178, v162
	v_add_f32_e32 v163, v179, v163
	v_cndmask_b32_e64 v200, 0, v179, s[18:19]
	v_add_f32_e32 v162, v214, v162
	v_add_f32_e32 v163, v215, v163
	v_cndmask_b32_e64 v201, v215, 0, s[6:7]
	v_add_f32_e32 v162, v216, v162
	v_add_f32_e32 v163, v217, v163
	v_cndmask_b32_e64 v203, 0, v215, s[6:7]
	v_add_f32_e32 v130, v130, v162
	v_add_f32_e32 v131, v131, v163
	v_cndmask_b32_e64 v204, v217, 0, s[8:9]
	v_cndmask_b32_e64 v205, 0, v217, s[8:9]
	v_cvt_pk_bf16_f32 v198, v198, v199
	v_cvt_pk_bf16_f32 v199, v201, v204
	v_cvt_pk_bf16_f32 v200, v202, v200
	v_cvt_pk_bf16_f32 v201, v203, v205
	s_setprio 1
	s_waitcnt lgkmcnt(11)
	v_mfma_f32_16x16x32_bf16 v[44:47], v[158:161], v[198:201], v[44:47]
	s_waitcnt lgkmcnt(10)
	v_mfma_f32_16x16x32_bf16 v[40:43], v[166:169], v[198:201], v[40:43]
	s_waitcnt lgkmcnt(9)
	v_mfma_f32_16x16x32_bf16 v[36:39], v[170:173], v[198:201], v[36:39]
	s_waitcnt lgkmcnt(8)
	v_mfma_f32_16x16x32_bf16 v[32:35], v[174:177], v[198:201], v[32:35]
	s_setprio 0
	ds_read2_b64 v[158:161], v181 offset0:134 offset1:138
	ds_read2_b64 v[166:169], v218 offset0:166 offset1:170
	ds_read2_b64 v[170:173], v219 offset0:198 offset1:202
	ds_read2_b64 v[174:177], v220 offset0:134 offset1:138
	ds_read_b128 v[198:201], v119 offset:23040
	ds_read_b128 v[202:205], v119 offset:23104
	v_add_u32_e32 v119, v148, v151
	ds_read_b128 v[206:209], v119 offset:18432
	ds_read_b128 v[210:213], v119 offset:18496
	v_add_u32_e32 v119, s66, v154
	v_add_u32_sdwa v162, s66, v144 dst_sel:DWORD dst_unused:UNUSED_PAD src0_sel:DWORD src1_sel:BYTE_1
	v_add_u32_sdwa v163, s66, v145 dst_sel:DWORD dst_unused:UNUSED_PAD src0_sel:DWORD src1_sel:BYTE_2
	v_add_u32_sdwa v178, s66, v145 dst_sel:DWORD dst_unused:UNUSED_PAD src0_sel:DWORD src1_sel:BYTE_3
	ds_read_b32 v119, v119 offset:41984
	ds_read_b32 v179, v162 offset:41984
	ds_read_b32 v214, v163 offset:41984
	ds_read_b32 v215, v178 offset:41984
	s_setprio 1
	s_waitcnt vmcnt(3) lgkmcnt(14)
	v_mfma_f32_16x16x32_bf16 v[182:185], v[182:185], v[96:99], 0
	s_waitcnt vmcnt(2)
	v_mfma_f32_16x16x32_bf16 v[182:185], v[186:189], v[100:103], v[182:185]
	v_mfma_f32_16x16x32_bf16 v[186:189], v[190:193], v[96:99], 0
	v_mfma_f32_16x16x32_bf16 v[186:189], v[194:197], v[100:103], v[186:189]
	s_setprio 0
	s_nop 6
	v_cndmask_b32_e64 v162, v186, v182, s[2:3]
	v_add_f32_e32 v136, v136, v162
	v_exp_f32_e32 v162, v136
	v_cndmask_b32_e64 v136, v187, v183, s[4:5]
	v_cndmask_b32_e64 v183, v184, v188, s[22:23]
	s_waitcnt lgkmcnt(13)
	v_add_f32_e32 v165, v165, v183
	v_exp_f32_e32 v190, v165
	v_cndmask_b32_e64 v165, v185, v189, s[24:25]
	v_add_f32_e32 v136, v223, v136
	s_waitcnt lgkmcnt(12)
	v_add_f32_e32 v165, v224, v165
	v_exp_f32_e32 v178, v136
	v_exp_f32_e32 v192, v165
	v_cndmask_b32_e64 v183, v190, 0, s[22:23]
	v_cndmask_b32_e64 v185, 0, v190, s[22:23]
	v_cndmask_b32_e64 v182, 0, v178, s[4:5]
	v_cndmask_b32_e64 v184, v192, 0, s[24:25]
	v_cndmask_b32_e64 v136, 0, v162, s[2:3]
	v_cndmask_b32_e64 v163, v162, 0, s[2:3]
	v_cndmask_b32_e64 v165, v178, 0, s[4:5]
	v_cndmask_b32_e64 v186, 0, v192, s[24:25]
	v_cvt_pk_bf16_f32 v182, v136, v182
	v_cvt_pk_bf16_f32 v183, v183, v184
	v_cvt_pk_bf16_f32 v184, v163, v165
	v_cvt_pk_bf16_f32 v185, v185, v186
	s_setprio 1
	s_waitcnt lgkmcnt(11)
	v_mfma_f32_16x16x32_bf16 v[28:31], v[158:161], v[182:185], v[28:31]
	s_waitcnt lgkmcnt(10)
	v_mfma_f32_16x16x32_bf16 v[24:27], v[166:169], v[182:185], v[24:27]
	s_waitcnt lgkmcnt(9)
	v_mfma_f32_16x16x32_bf16 v[20:23], v[170:173], v[182:185], v[20:23]
	s_waitcnt lgkmcnt(8)
	v_mfma_f32_16x16x32_bf16 v[16:19], v[174:177], v[182:185], v[16:19]
	s_setprio 0
	ds_read2_b64 v[158:161], v220 offset0:136 offset1:140
	ds_read2_b64 v[166:169], v219 offset0:200 offset1:204
	ds_read2_b64 v[170:173], v218 offset0:168 offset1:172
	ds_read2_b64 v[174:177], v181 offset0:136 offset1:140
	s_setprio 1
	s_waitcnt vmcnt(1) lgkmcnt(11)
	v_mfma_f32_16x16x32_bf16 v[182:185], v[198:201], v[104:107], 0
	s_waitcnt lgkmcnt(9)
	v_mfma_f32_16x16x32_bf16 v[186:189], v[206:209], v[104:107], 0
	s_waitcnt vmcnt(0)
	v_mfma_f32_16x16x32_bf16 v[182:185], v[202:205], v[108:111], v[182:185]
	s_waitcnt lgkmcnt(8)
	v_mfma_f32_16x16x32_bf16 v[186:189], v[210:213], v[108:111], v[186:189]
	s_setprio 0
	s_nop 6
	v_cndmask_b32_e64 v136, v182, v186, s[26:27]
	s_waitcnt lgkmcnt(7)
	v_add_f32_e32 v119, v119, v136
	v_exp_f32_e32 v163, v119
	v_cndmask_b32_e64 v119, v183, v187, s[28:29]
	v_cndmask_b32_e64 v181, v184, v188, s[30:31]
	s_waitcnt lgkmcnt(6)
	v_add_f32_e32 v119, v179, v119
	s_waitcnt lgkmcnt(5)
	v_add_f32_e32 v181, v214, v181
	v_exp_f32_e32 v179, v119
	v_exp_f32_e32 v191, v181
	v_cndmask_b32_e64 v181, v185, v189, s[34:35]
	s_waitcnt lgkmcnt(4)
	v_add_f32_e32 v181, v215, v181
	v_exp_f32_e32 v193, v181
	v_cndmask_b32_e64 v119, v163, 0, s[26:27]
	v_cndmask_b32_e64 v136, 0, v163, s[26:27]
	v_add_f32_e32 v162, 0, v162
	v_add_f32_e32 v163, 0, v163
	v_cndmask_b32_e64 v183, v191, 0, s[30:31]
	v_add_f32_e32 v162, v178, v162
	v_add_f32_e32 v163, v179, v163
	v_cndmask_b32_e64 v185, 0, v191, s[30:31]
	v_add_f32_e32 v162, v190, v162
	v_add_f32_e32 v163, v191, v163
	v_cndmask_b32_e64 v184, v193, 0, s[34:35]
	v_add_f32_e32 v162, v192, v162
	v_add_f32_e32 v163, v193, v163
	v_cndmask_b32_e64 v165, v179, 0, s[28:29]
	v_add_f32_e32 v124, v124, v162
	v_add_f32_e32 v125, v125, v163
	v_cndmask_b32_e64 v181, 0, v179, s[28:29]
	v_cndmask_b32_e64 v186, 0, v193, s[34:35]
	v_cvt_pk_bf16_f32 v182, v119, v165
	v_cvt_pk_bf16_f32 v183, v183, v184
	v_cvt_pk_bf16_f32 v184, v136, v181
	v_cvt_pk_bf16_f32 v185, v185, v186
	s_setprio 1
	s_waitcnt lgkmcnt(0)
	v_mfma_f32_16x16x32_bf16 v[12:15], v[174:177], v[182:185], v[12:15]
	v_mfma_f32_16x16x32_bf16 v[8:11], v[170:173], v[182:185], v[8:11]
	v_mfma_f32_16x16x32_bf16 v[4:7], v[166:169], v[182:185], v[4:7]
	v_mfma_f32_16x16x32_bf16 v[0:3], v[158:161], v[182:185], v[0:3]
	s_setprio 0

.LBB0_559:
	s_or_b64 exec, exec, s[6:7]
	s_mov_b64 s[6:7], exec
	v_mbcnt_lo_u32_b32 v0, s6, 0
	v_mbcnt_hi_u32_b32 v0, s7, v0
	v_cmp_eq_u32_e32 vcc, 0, v0
	s_waitcnt vmcnt(0)
	buffer_inv sc1
	s_and_saveexec_b64 s[8:9], vcc
	s_cbranch_execz .LBB0_561
	s_bcnt1_i32_b64 s6, s[6:7]
	v_mov_b32_e32 v0, 0x2000
	v_mov_b32_e32 v1, s6
.LBB0_561:
	s_or_b64 exec, exec, s[8:9]
	s_waitcnt vmcnt(0)

.LBB0_590:
	s_add_i32 s70, s52, -3
	s_cmp_ge_u32 s70, s38
	s_cselect_b64 s[66:67], -1, 0
	s_cmp_lt_u32 s70, s39
	s_cselect_b64 s[72:73], -1, 0
	s_and_b64 s[66:67], s[66:67], s[72:73]
	s_andn2_b64 vcc, exec, s[66:67]
	s_cbranch_vccnz .LBB0_592
	v_add_u32_e32 v178, v150, v149
	v_add_u32_e32 v181, 0x2000, v178
	v_add_u32_e32 v218, 0x2800, v178
	v_add_u32_e32 v219, 0x3000, v178
	v_add_u32_e32 v178, v150, v151
	v_add_u32_e32 v119, v148, v149
	v_add_u32_e32 v136, s68, v152
	v_add_u32_sdwa v163, s68, v144 dst_sel:DWORD dst_unused:UNUSED_PAD src0_sel:DWORD src1_sel:BYTE_2
	v_add_u32_sdwa v165, s68, v144 dst_sel:DWORD dst_unused:UNUSED_PAD src0_sel:DWORD src1_sel:BYTE_3
	v_add_u32_e32 v220, 0x2000, v178
	v_add_u32_sdwa v179, s68, v142 dst_sel:DWORD dst_unused:UNUSED_PAD src0_sel:DWORD src1_sel:BYTE_1
	ds_read_b128 v[158:161], v119
	ds_read_b128 v[166:169], v119 offset:64
	ds_read_b128 v[170:173], v119 offset:2304
	ds_read_b128 v[174:177], v119 offset:2368
	v_add_u32_e32 v162, s68, v153
	ds_read2_b64 v[182:185], v181 offset0:128 offset1:132
	ds_read2_b64 v[186:189], v218 offset0:160 offset1:164
	ds_read2_b64 v[190:193], v219 offset0:192 offset1:196
	ds_read2_b64 v[194:197], v220 offset0:128 offset1:132
	ds_read_b128 v[198:201], v119 offset:1152
	ds_read_b128 v[202:205], v119 offset:1216
	ds_read_b128 v[206:209], v119 offset:3456
	ds_read_b128 v[210:213], v119 offset:3520
	v_add_u32_e32 v178, s68, v155
	v_add_u32_sdwa v214, s68, v143 dst_sel:DWORD dst_unused:UNUSED_PAD src0_sel:DWORD src1_sel:BYTE_2
	v_add_u32_sdwa v215, s68, v143 dst_sel:DWORD dst_unused:UNUSED_PAD src0_sel:DWORD src1_sel:BYTE_3
	ds_read_b32 v136, v136 offset:41856
	ds_read_b32 v216, v162 offset:41856
	ds_read_b32 v163, v163 offset:41856
	ds_read_b32 v165, v165 offset:41856
	ds_read_b32 v217, v178 offset:41856
	ds_read_b32 v179, v179 offset:41856
	ds_read_b32 v221, v214 offset:41856
	ds_read_b32 v222, v215 offset:41856
	s_setprio 1
	s_waitcnt vmcnt(7) lgkmcnt(14)
	v_mfma_f32_16x16x32_bf16 v[158:161], v[158:161], v[80:83], 0
	s_waitcnt vmcnt(6)
	v_mfma_f32_16x16x32_bf16 v[158:161], v[166:169], v[84:87], v[158:161]
	v_mfma_f32_16x16x32_bf16 v[166:169], v[170:173], v[80:83], 0
	v_mfma_f32_16x16x32_bf16 v[166:169], v[174:177], v[84:87], v[166:169]
	s_setprio 0
	s_nop 6
	v_cndmask_b32_e64 v158, v166, v158, s[20:21]
	s_waitcnt lgkmcnt(7)
	v_add_f32_e32 v136, v136, v158
	v_exp_f32_e32 v162, v136
	v_cndmask_b32_e64 v136, v159, v167, s[10:11]
	v_cndmask_b32_e64 v159, v160, v168, s[12:13]
	s_waitcnt lgkmcnt(5)
	v_add_f32_e32 v159, v163, v159
	v_add_f32_e32 v136, v216, v136
	v_exp_f32_e32 v214, v159
	v_cndmask_b32_e64 v159, v161, v169, s[14:15]
	v_exp_f32_e32 v178, v136
	s_waitcnt lgkmcnt(4)
	v_add_f32_e32 v159, v165, v159
	v_exp_f32_e32 v216, v159
	v_cndmask_b32_e64 v159, v214, 0, s[12:13]
	v_cndmask_b32_e64 v158, v178, 0, s[10:11]
	v_cndmask_b32_e64 v160, 0, v178, s[10:11]
	v_cndmask_b32_e64 v161, 0, v214, s[12:13]
	v_cndmask_b32_e64 v136, 0, v162, s[20:21]
	v_cndmask_b32_e64 v166, v162, 0, s[20:21]
	v_cndmask_b32_e64 v163, v216, 0, s[14:15]
	v_cndmask_b32_e64 v165, 0, v216, s[14:15]
	v_cvt_pk_bf16_f32 v158, v136, v158
	v_cvt_pk_bf16_f32 v159, v159, v163
	v_cvt_pk_bf16_f32 v160, v166, v160
	v_cvt_pk_bf16_f32 v161, v161, v165
	s_setprio 1
	v_mfma_f32_16x16x32_bf16 v[60:63], v[182:185], v[158:161], v[60:63]
	v_mfma_f32_16x16x32_bf16 v[56:59], v[186:189], v[158:161], v[56:59]
	v_mfma_f32_16x16x32_bf16 v[52:55], v[190:193], v[158:161], v[52:55]
	v_mfma_f32_16x16x32_bf16 v[48:51], v[194:197], v[158:161], v[48:51]
	s_setprio 0
	ds_read2_b64 v[158:161], v181 offset0:130 offset1:134
	ds_read2_b64 v[166:169], v218 offset0:162 offset1:166
	ds_read2_b64 v[170:173], v219 offset0:194 offset1:198
	ds_read2_b64 v[174:177], v220 offset0:130 offset1:134
	ds_read_b128 v[182:185], v119 offset:3456
	ds_read_b128 v[186:189], v119 offset:3520
	ds_read_b128 v[190:193], v119 offset:5760
	ds_read_b128 v[194:197], v119 offset:5824
	v_add_u32_e32 v136, s68, v156
	v_add_u32_sdwa v165, s68, v141 dst_sel:DWORD dst_unused:UNUSED_PAD src0_sel:DWORD src1_sel:BYTE_2
	v_add_u32_sdwa v163, s68, v140 dst_sel:DWORD dst_unused:UNUSED_PAD src0_sel:DWORD src1_sel:BYTE_1
	v_add_u32_sdwa v215, s68, v141 dst_sel:DWORD dst_unused:UNUSED_PAD src0_sel:DWORD src1_sel:BYTE_3
	ds_read_b32 v136, v136 offset:41856
	ds_read_b32 v223, v163 offset:41856
	ds_read_b32 v165, v165 offset:41856
	ds_read_b32 v224, v215 offset:41856
	s_setprio 1
	s_waitcnt vmcnt(5)
	v_mfma_f32_16x16x32_bf16 v[198:201], v[198:201], v[88:91], 0
	s_waitcnt vmcnt(4)
	v_mfma_f32_16x16x32_bf16 v[198:201], v[202:205], v[92:95], v[198:201]
	v_mfma_f32_16x16x32_bf16 v[202:205], v[206:209], v[88:91], 0
	v_mfma_f32_16x16x32_bf16 v[202:205], v[210:213], v[92:95], v[202:205]
	s_setprio 0
	s_nop 6
	v_cndmask_b32_e64 v163, v198, v202, s[16:17]
	s_waitcnt lgkmcnt(14)
	v_add_f32_e32 v163, v217, v163
	v_cndmask_b32_e64 v198, v199, v203, s[18:19]
	v_cndmask_b32_e64 v200, v200, v204, s[6:7]
	v_exp_f32_e32 v163, v163
	v_add_f32_e32 v179, v179, v198
	s_waitcnt lgkmcnt(13)
	v_add_f32_e32 v200, v221, v200
	v_exp_f32_e32 v179, v179
	v_exp_f32_e32 v215, v200
	v_cndmask_b32_e64 v200, v201, v205, s[8:9]
	s_waitcnt lgkmcnt(12)
	v_add_f32_e32 v200, v222, v200
	v_exp_f32_e32 v217, v200
	v_cndmask_b32_e64 v198, v163, 0, s[16:17]
	v_cndmask_b32_e64 v202, 0, v163, s[16:17]
	v_add_f32_e32 v162, 0, v162
	v_add_f32_e32 v163, 0, v163
	v_cndmask_b32_e64 v199, v179, 0, s[18:19]
	v_add_f32_e32 v162, v178, v162
	v_add_f32_e32 v163, v179, v163
	v_cndmask_b32_e64 v200, 0, v179, s[18:19]
	v_add_f32_e32 v162, v214, v162
	v_add_f32_e32 v163, v215, v163
	v_cndmask_b32_e64 v201, v215, 0, s[6:7]
	v_add_f32_e32 v162, v216, v162
	v_add_f32_e32 v163, v217, v163
	v_cndmask_b32_e64 v203, 0, v215, s[6:7]
	v_add_f32_e32 v130, v130, v162
	v_add_f32_e32 v131, v131, v163
	v_cndmask_b32_e64 v204, v217, 0, s[8:9]
	v_cndmask_b32_e64 v205, 0, v217, s[8:9]
	v_cvt_pk_bf16_f32 v198, v198, v199
	v_cvt_pk_bf16_f32 v199, v201, v204
	v_cvt_pk_bf16_f32 v200, v202, v200
	v_cvt_pk_bf16_f32 v201, v203, v205
	s_setprio 1
	s_waitcnt lgkmcnt(11)
	v_mfma_f32_16x16x32_bf16 v[44:47], v[158:161], v[198:201], v[44:47]
	s_waitcnt lgkmcnt(10)
	v_mfma_f32_16x16x32_bf16 v[40:43], v[166:169], v[198:201], v[40:43]
	s_waitcnt lgkmcnt(9)
	v_mfma_f32_16x16x32_bf16 v[36:39], v[170:173], v[198:201], v[36:39]
	s_waitcnt lgkmcnt(8)
	v_mfma_f32_16x16x32_bf16 v[32:35], v[174:177], v[198:201], v[32:35]
	s_setprio 0
	ds_read2_b64 v[158:161], v181 offset0:134 offset1:138
	ds_read2_b64 v[166:169], v218 offset0:166 offset1:170
	ds_read2_b64 v[170:173], v219 offset0:198 offset1:202
	ds_read2_b64 v[174:177], v220 offset0:134 offset1:138
	ds_read_b128 v[198:201], v119 offset:4608
	ds_read_b128 v[202:205], v119 offset:4672
	v_add_u32_e32 v119, v148, v151
	ds_read_b128 v[206:209], v119
	ds_read_b128 v[210:213], v119 offset:64
	v_add_u32_e32 v119, s68, v154
	v_add_u32_sdwa v162, s68, v145 dst_sel:DWORD dst_unused:UNUSED_PAD src0_sel:DWORD src1_sel:BYTE_1
	v_add_u32_sdwa v163, s68, v146 dst_sel:DWORD dst_unused:UNUSED_PAD src0_sel:DWORD src1_sel:BYTE_2
	v_add_u32_sdwa v178, s68, v146 dst_sel:DWORD dst_unused:UNUSED_PAD src0_sel:DWORD src1_sel:BYTE_3
	ds_read_b32 v119, v119 offset:41856
	ds_read_b32 v179, v162 offset:41856
	ds_read_b32 v214, v163 offset:41856
	ds_read_b32 v215, v178 offset:41856
	s_setprio 1
	s_waitcnt vmcnt(3) lgkmcnt(14)
	v_mfma_f32_16x16x32_bf16 v[182:185], v[182:185], v[96:99], 0
	s_waitcnt vmcnt(2)
	v_mfma_f32_16x16x32_bf16 v[182:185], v[186:189], v[100:103], v[182:185]
	v_mfma_f32_16x16x32_bf16 v[186:189], v[190:193], v[96:99], 0
	v_mfma_f32_16x16x32_bf16 v[186:189], v[194:197], v[100:103], v[186:189]
	s_setprio 0
	s_nop 6
	v_cndmask_b32_e64 v162, v186, v182, s[2:3]
	v_add_f32_e32 v136, v136, v162
	v_exp_f32_e32 v162, v136
	v_cndmask_b32_e64 v136, v187, v183, s[4:5]
	v_cndmask_b32_e64 v183, v184, v188, s[22:23]
	s_waitcnt lgkmcnt(13)
	v_add_f32_e32 v165, v165, v183
	v_exp_f32_e32 v190, v165
	v_cndmask_b32_e64 v165, v185, v189, s[24:25]
	v_add_f32_e32 v136, v223, v136
	s_waitcnt lgkmcnt(12)
	v_add_f32_e32 v165, v224, v165
	v_exp_f32_e32 v178, v136
	v_exp_f32_e32 v192, v165
	v_cndmask_b32_e64 v183, v190, 0, s[22:23]
	v_cndmask_b32_e64 v185, 0, v190, s[22:23]
	v_cndmask_b32_e64 v182, 0, v178, s[4:5]
	v_cndmask_b32_e64 v184, v192, 0, s[24:25]
	v_cndmask_b32_e64 v136, 0, v162, s[2:3]
	v_cndmask_b32_e64 v163, v162, 0, s[2:3]
	v_cndmask_b32_e64 v165, v178, 0, s[4:5]
	v_cndmask_b32_e64 v186, 0, v192, s[24:25]
	v_cvt_pk_bf16_f32 v182, v136, v182
	v_cvt_pk_bf16_f32 v183, v183, v184
	v_cvt_pk_bf16_f32 v184, v163, v165
	v_cvt_pk_bf16_f32 v185, v185, v186
	s_setprio 1
	s_waitcnt lgkmcnt(11)
	v_mfma_f32_16x16x32_bf16 v[28:31], v[158:161], v[182:185], v[28:31]
	s_waitcnt lgkmcnt(10)
	v_mfma_f32_16x16x32_bf16 v[24:27], v[166:169], v[182:185], v[24:27]
	s_waitcnt lgkmcnt(9)
	v_mfma_f32_16x16x32_bf16 v[20:23], v[170:173], v[182:185], v[20:23]
	s_waitcnt lgkmcnt(8)
	v_mfma_f32_16x16x32_bf16 v[16:19], v[174:177], v[182:185], v[16:19]
	s_setprio 0
	ds_read2_b64 v[158:161], v220 offset0:136 offset1:140
	ds_read2_b64 v[166:169], v219 offset0:200 offset1:204
	ds_read2_b64 v[170:173], v218 offset0:168 offset1:172
	ds_read2_b64 v[174:177], v181 offset0:136 offset1:140
	s_setprio 1
	s_waitcnt vmcnt(1) lgkmcnt(11)
	v_mfma_f32_16x16x32_bf16 v[182:185], v[198:201], v[104:107], 0
	s_waitcnt lgkmcnt(9)
	v_mfma_f32_16x16x32_bf16 v[186:189], v[206:209], v[104:107], 0
	s_waitcnt vmcnt(0)
	v_mfma_f32_16x16x32_bf16 v[182:185], v[202:205], v[108:111], v[182:185]
	s_waitcnt lgkmcnt(8)
	v_mfma_f32_16x16x32_bf16 v[186:189], v[210:213], v[108:111], v[186:189]
	s_setprio 0
	s_nop 6
	v_cndmask_b32_e64 v136, v182, v186, s[26:27]
	s_waitcnt lgkmcnt(7)
	v_add_f32_e32 v119, v119, v136
	v_exp_f32_e32 v163, v119
	v_cndmask_b32_e64 v119, v183, v187, s[28:29]
	v_cndmask_b32_e64 v181, v184, v188, s[30:31]
	s_waitcnt lgkmcnt(6)
	v_add_f32_e32 v119, v179, v119
	s_waitcnt lgkmcnt(5)
	v_add_f32_e32 v181, v214, v181
	v_exp_f32_e32 v179, v119
	v_exp_f32_e32 v191, v181
	v_cndmask_b32_e64 v181, v185, v189, s[34:35]
	s_waitcnt lgkmcnt(4)
	v_add_f32_e32 v181, v215, v181
	v_exp_f32_e32 v193, v181
	v_cndmask_b32_e64 v119, v163, 0, s[26:27]
	v_cndmask_b32_e64 v136, 0, v163, s[26:27]
	v_add_f32_e32 v162, 0, v162
	v_add_f32_e32 v163, 0, v163
	v_cndmask_b32_e64 v183, v191, 0, s[30:31]
	v_add_f32_e32 v162, v178, v162
	v_add_f32_e32 v163, v179, v163
	v_cndmask_b32_e64 v185, 0, v191, s[30:31]
	v_add_f32_e32 v162, v190, v162
	v_add_f32_e32 v163, v191, v163
	v_cndmask_b32_e64 v184, v193, 0, s[34:35]
	v_add_f32_e32 v162, v192, v162
	v_add_f32_e32 v163, v193, v163
	v_cndmask_b32_e64 v165, v179, 0, s[28:29]
	v_add_f32_e32 v124, v124, v162
	v_add_f32_e32 v125, v125, v163
	v_cndmask_b32_e64 v181, 0, v179, s[28:29]
	v_cndmask_b32_e64 v186, 0, v193, s[34:35]
	v_cvt_pk_bf16_f32 v182, v119, v165
	v_cvt_pk_bf16_f32 v183, v183, v184
	v_cvt_pk_bf16_f32 v184, v136, v181
	v_cvt_pk_bf16_f32 v185, v185, v186
	s_setprio 1
	s_waitcnt lgkmcnt(0)
	v_mfma_f32_16x16x32_bf16 v[12:15], v[174:177], v[182:185], v[12:15]
	v_mfma_f32_16x16x32_bf16 v[8:11], v[170:173], v[182:185], v[8:11]
	v_mfma_f32_16x16x32_bf16 v[4:7], v[166:169], v[182:185], v[4:7]
	v_mfma_f32_16x16x32_bf16 v[0:3], v[158:161], v[182:185], v[0:3]
	s_setprio 0

.LBB0_597:
	s_add_i32 s66, s52, -2
	s_cmp_ge_u32 s66, s38
	s_cselect_b64 s[70:71], -1, 0
	s_cmp_lt_u32 s66, s39
	s_cselect_b64 s[72:73], -1, 0
	s_and_b64 s[70:71], s[70:71], s[72:73]
	s_andn2_b64 vcc, exec, s[70:71]
	s_cbranch_vccnz .LBB0_599
	v_add_u32_e32 v178, v150, v149
	v_add_u32_e32 v181, 0x6800, v178
	v_add_u32_e32 v218, 0x7000, v178
	v_add_u32_e32 v219, 0x7800, v178
	v_add_u32_e32 v178, v150, v151
	v_add_u32_e32 v119, v148, v149
	v_add_u32_e32 v136, s68, v152
	v_add_u32_sdwa v163, s68, v144 dst_sel:DWORD dst_unused:UNUSED_PAD src0_sel:DWORD src1_sel:BYTE_2
	v_add_u32_sdwa v165, s68, v144 dst_sel:DWORD dst_unused:UNUSED_PAD src0_sel:DWORD src1_sel:BYTE_3
	v_add_u32_e32 v220, 0x6800, v178
	v_add_u32_sdwa v179, s68, v142 dst_sel:DWORD dst_unused:UNUSED_PAD src0_sel:DWORD src1_sel:BYTE_1
	ds_read_b128 v[158:161], v119 offset:18432
	ds_read_b128 v[166:169], v119 offset:18496
	ds_read_b128 v[170:173], v119 offset:20736
	ds_read_b128 v[174:177], v119 offset:20800
	v_add_u32_e32 v162, s68, v153
	ds_read2_b64 v[182:185], v181 offset0:128 offset1:132
	ds_read2_b64 v[186:189], v218 offset0:160 offset1:164
	ds_read2_b64 v[190:193], v219 offset0:192 offset1:196
	ds_read2_b64 v[194:197], v220 offset0:128 offset1:132
	ds_read_b128 v[198:201], v119 offset:19584
	ds_read_b128 v[202:205], v119 offset:19648
	ds_read_b128 v[206:209], v119 offset:21888
	ds_read_b128 v[210:213], v119 offset:21952
	v_add_u32_e32 v178, s68, v155
	v_add_u32_sdwa v214, s68, v143 dst_sel:DWORD dst_unused:UNUSED_PAD src0_sel:DWORD src1_sel:BYTE_2
	v_add_u32_sdwa v215, s68, v143 dst_sel:DWORD dst_unused:UNUSED_PAD src0_sel:DWORD src1_sel:BYTE_3
	ds_read_b32 v136, v136 offset:41984
	ds_read_b32 v216, v162 offset:41984
	ds_read_b32 v163, v163 offset:41984
	ds_read_b32 v165, v165 offset:41984
	ds_read_b32 v217, v178 offset:41984
	ds_read_b32 v179, v179 offset:41984
	ds_read_b32 v221, v214 offset:41984
	ds_read_b32 v222, v215 offset:41984
	s_setprio 1
	s_waitcnt vmcnt(7) lgkmcnt(14)
	v_mfma_f32_16x16x32_bf16 v[158:161], v[158:161], v[80:83], 0
	s_waitcnt vmcnt(6)
	v_mfma_f32_16x16x32_bf16 v[158:161], v[166:169], v[84:87], v[158:161]
	v_mfma_f32_16x16x32_bf16 v[166:169], v[170:173], v[80:83], 0
	v_mfma_f32_16x16x32_bf16 v[166:169], v[174:177], v[84:87], v[166:169]
	s_setprio 0
	s_nop 6
	v_cndmask_b32_e64 v158, v166, v158, s[20:21]
	s_waitcnt lgkmcnt(7)
	v_add_f32_e32 v136, v136, v158
	v_exp_f32_e32 v162, v136
	v_cndmask_b32_e64 v136, v159, v167, s[10:11]
	v_cndmask_b32_e64 v159, v160, v168, s[12:13]
	s_waitcnt lgkmcnt(5)
	v_add_f32_e32 v159, v163, v159
	v_add_f32_e32 v136, v216, v136
	v_exp_f32_e32 v214, v159
	v_cndmask_b32_e64 v159, v161, v169, s[14:15]
	v_exp_f32_e32 v178, v136
	s_waitcnt lgkmcnt(4)
	v_add_f32_e32 v159, v165, v159
	v_exp_f32_e32 v216, v159
	v_cndmask_b32_e64 v159, v214, 0, s[12:13]
	v_cndmask_b32_e64 v158, v178, 0, s[10:11]
	v_cndmask_b32_e64 v160, 0, v178, s[10:11]
	v_cndmask_b32_e64 v161, 0, v214, s[12:13]
	v_cndmask_b32_e64 v136, 0, v162, s[20:21]
	v_cndmask_b32_e64 v166, v162, 0, s[20:21]
	v_cndmask_b32_e64 v163, v216, 0, s[14:15]
	v_cndmask_b32_e64 v165, 0, v216, s[14:15]
	v_cvt_pk_bf16_f32 v158, v136, v158
	v_cvt_pk_bf16_f32 v159, v159, v163
	v_cvt_pk_bf16_f32 v160, v166, v160
	v_cvt_pk_bf16_f32 v161, v161, v165
	s_setprio 1
	v_mfma_f32_16x16x32_bf16 v[60:63], v[182:185], v[158:161], v[60:63]
	v_mfma_f32_16x16x32_bf16 v[56:59], v[186:189], v[158:161], v[56:59]
	v_mfma_f32_16x16x32_bf16 v[52:55], v[190:193], v[158:161], v[52:55]
	v_mfma_f32_16x16x32_bf16 v[48:51], v[194:197], v[158:161], v[48:51]
	s_setprio 0
	ds_read2_b64 v[158:161], v181 offset0:130 offset1:134
	ds_read2_b64 v[166:169], v218 offset0:162 offset1:166
	ds_read2_b64 v[170:173], v219 offset0:194 offset1:198
	ds_read2_b64 v[174:177], v220 offset0:130 offset1:134
	ds_read_b128 v[182:185], v119 offset:21888
	ds_read_b128 v[186:189], v119 offset:21952
	ds_read_b128 v[190:193], v119 offset:24192
	ds_read_b128 v[194:197], v119 offset:24256
	v_add_u32_e32 v136, s68, v156
	v_add_u32_sdwa v165, s68, v141 dst_sel:DWORD dst_unused:UNUSED_PAD src0_sel:DWORD src1_sel:BYTE_2
	v_add_u32_sdwa v163, s68, v140 dst_sel:DWORD dst_unused:UNUSED_PAD src0_sel:DWORD src1_sel:BYTE_1
	v_add_u32_sdwa v215, s68, v141 dst_sel:DWORD dst_unused:UNUSED_PAD src0_sel:DWORD src1_sel:BYTE_3
	ds_read_b32 v136, v136 offset:41984
	ds_read_b32 v223, v163 offset:41984
	ds_read_b32 v165, v165 offset:41984
	ds_read_b32 v224, v215 offset:41984
	s_setprio 1
	s_waitcnt vmcnt(5)
	v_mfma_f32_16x16x32_bf16 v[198:201], v[198:201], v[88:91], 0
	s_waitcnt vmcnt(4)
	v_mfma_f32_16x16x32_bf16 v[198:201], v[202:205], v[92:95], v[198:201]
	v_mfma_f32_16x16x32_bf16 v[202:205], v[206:209], v[88:91], 0
	v_mfma_f32_16x16x32_bf16 v[202:205], v[210:213], v[92:95], v[202:205]
	s_setprio 0
	s_nop 6
	v_cndmask_b32_e64 v163, v198, v202, s[16:17]
	s_waitcnt lgkmcnt(14)
	v_add_f32_e32 v163, v217, v163
	v_cndmask_b32_e64 v198, v199, v203, s[18:19]
	v_cndmask_b32_e64 v200, v200, v204, s[6:7]
	v_exp_f32_e32 v163, v163
	v_add_f32_e32 v179, v179, v198
	s_waitcnt lgkmcnt(13)
	v_add_f32_e32 v200, v221, v200
	v_exp_f32_e32 v179, v179
	v_exp_f32_e32 v215, v200
	v_cndmask_b32_e64 v200, v201, v205, s[8:9]
	s_waitcnt lgkmcnt(12)
	v_add_f32_e32 v200, v222, v200
	v_exp_f32_e32 v217, v200
	v_cndmask_b32_e64 v198, v163, 0, s[16:17]
	v_cndmask_b32_e64 v202, 0, v163, s[16:17]
	v_add_f32_e32 v162, 0, v162
	v_add_f32_e32 v163, 0, v163
	v_cndmask_b32_e64 v199, v179, 0, s[18:19]
	v_add_f32_e32 v162, v178, v162
	v_add_f32_e32 v163, v179, v163
	v_cndmask_b32_e64 v200, 0, v179, s[18:19]
	v_add_f32_e32 v162, v214, v162
	v_add_f32_e32 v163, v215, v163
	v_cndmask_b32_e64 v201, v215, 0, s[6:7]
	v_add_f32_e32 v162, v216, v162
	v_add_f32_e32 v163, v217, v163
	v_cndmask_b32_e64 v203, 0, v215, s[6:7]
	v_add_f32_e32 v130, v130, v162
	v_add_f32_e32 v131, v131, v163
	v_cndmask_b32_e64 v204, v217, 0, s[8:9]
	v_cndmask_b32_e64 v205, 0, v217, s[8:9]
	v_cvt_pk_bf16_f32 v198, v198, v199
	v_cvt_pk_bf16_f32 v199, v201, v204
	v_cvt_pk_bf16_f32 v200, v202, v200
	v_cvt_pk_bf16_f32 v201, v203, v205
	s_setprio 1
	s_waitcnt lgkmcnt(11)
	v_mfma_f32_16x16x32_bf16 v[44:47], v[158:161], v[198:201], v[44:47]
	s_waitcnt lgkmcnt(10)
	v_mfma_f32_16x16x32_bf16 v[40:43], v[166:169], v[198:201], v[40:43]
	s_waitcnt lgkmcnt(9)
	v_mfma_f32_16x16x32_bf16 v[36:39], v[170:173], v[198:201], v[36:39]
	s_waitcnt lgkmcnt(8)
	v_mfma_f32_16x16x32_bf16 v[32:35], v[174:177], v[198:201], v[32:35]
	s_setprio 0
	ds_read2_b64 v[158:161], v181 offset0:134 offset1:138
	ds_read2_b64 v[166:169], v218 offset0:166 offset1:170
	ds_read2_b64 v[170:173], v219 offset0:198 offset1:202
	ds_read2_b64 v[174:177], v220 offset0:134 offset1:138
	ds_read_b128 v[198:201], v119 offset:23040
	ds_read_b128 v[202:205], v119 offset:23104
	v_add_u32_e32 v119, v148, v151
	ds_read_b128 v[206:209], v119 offset:18432
	ds_read_b128 v[210:213], v119 offset:18496
	v_add_u32_e32 v119, s68, v154
	v_add_u32_sdwa v162, s68, v145 dst_sel:DWORD dst_unused:UNUSED_PAD src0_sel:DWORD src1_sel:BYTE_1
	v_add_u32_sdwa v163, s68, v146 dst_sel:DWORD dst_unused:UNUSED_PAD src0_sel:DWORD src1_sel:BYTE_2
	v_add_u32_sdwa v178, s68, v146 dst_sel:DWORD dst_unused:UNUSED_PAD src0_sel:DWORD src1_sel:BYTE_3
	ds_read_b32 v119, v119 offset:41984
	ds_read_b32 v179, v162 offset:41984
	ds_read_b32 v214, v163 offset:41984
	ds_read_b32 v215, v178 offset:41984
	s_setprio 1
	s_waitcnt vmcnt(3) lgkmcnt(14)
	v_mfma_f32_16x16x32_bf16 v[182:185], v[182:185], v[96:99], 0
	s_waitcnt vmcnt(2)
	v_mfma_f32_16x16x32_bf16 v[182:185], v[186:189], v[100:103], v[182:185]
	v_mfma_f32_16x16x32_bf16 v[186:189], v[190:193], v[96:99], 0
	v_mfma_f32_16x16x32_bf16 v[186:189], v[194:197], v[100:103], v[186:189]
	s_setprio 0
	s_nop 6
	v_cndmask_b32_e64 v162, v186, v182, s[2:3]
	v_add_f32_e32 v136, v136, v162
	v_exp_f32_e32 v162, v136
	v_cndmask_b32_e64 v136, v187, v183, s[4:5]
	v_cndmask_b32_e64 v183, v184, v188, s[22:23]
	s_waitcnt lgkmcnt(13)
	v_add_f32_e32 v165, v165, v183
	v_exp_f32_e32 v190, v165
	v_cndmask_b32_e64 v165, v185, v189, s[24:25]
	v_add_f32_e32 v136, v223, v136
	s_waitcnt lgkmcnt(12)
	v_add_f32_e32 v165, v224, v165
	v_exp_f32_e32 v178, v136
	v_exp_f32_e32 v192, v165
	v_cndmask_b32_e64 v183, v190, 0, s[22:23]
	v_cndmask_b32_e64 v185, 0, v190, s[22:23]
	v_cndmask_b32_e64 v182, 0, v178, s[4:5]
	v_cndmask_b32_e64 v184, v192, 0, s[24:25]
	v_cndmask_b32_e64 v136, 0, v162, s[2:3]
	v_cndmask_b32_e64 v163, v162, 0, s[2:3]
	v_cndmask_b32_e64 v165, v178, 0, s[4:5]
	v_cndmask_b32_e64 v186, 0, v192, s[24:25]
	v_cvt_pk_bf16_f32 v182, v136, v182
	v_cvt_pk_bf16_f32 v183, v183, v184
	v_cvt_pk_bf16_f32 v184, v163, v165
	v_cvt_pk_bf16_f32 v185, v185, v186
	s_setprio 1
	s_waitcnt lgkmcnt(11)
	v_mfma_f32_16x16x32_bf16 v[28:31], v[158:161], v[182:185], v[28:31]
	s_waitcnt lgkmcnt(10)
	v_mfma_f32_16x16x32_bf16 v[24:27], v[166:169], v[182:185], v[24:27]
	s_waitcnt lgkmcnt(9)
	v_mfma_f32_16x16x32_bf16 v[20:23], v[170:173], v[182:185], v[20:23]
	s_waitcnt lgkmcnt(8)
	v_mfma_f32_16x16x32_bf16 v[16:19], v[174:177], v[182:185], v[16:19]
	s_setprio 0
	ds_read2_b64 v[158:161], v220 offset0:136 offset1:140
	ds_read2_b64 v[166:169], v219 offset0:200 offset1:204
	ds_read2_b64 v[170:173], v218 offset0:168 offset1:172
	ds_read2_b64 v[174:177], v181 offset0:136 offset1:140
	s_setprio 1
	s_waitcnt vmcnt(1) lgkmcnt(11)
	v_mfma_f32_16x16x32_bf16 v[182:185], v[198:201], v[104:107], 0
	s_waitcnt lgkmcnt(9)
	v_mfma_f32_16x16x32_bf16 v[186:189], v[206:209], v[104:107], 0
	s_waitcnt vmcnt(0)
	v_mfma_f32_16x16x32_bf16 v[182:185], v[202:205], v[108:111], v[182:185]
	s_waitcnt lgkmcnt(8)
	v_mfma_f32_16x16x32_bf16 v[186:189], v[210:213], v[108:111], v[186:189]
	s_setprio 0
	s_nop 6
	v_cndmask_b32_e64 v136, v182, v186, s[26:27]
	s_waitcnt lgkmcnt(7)
	v_add_f32_e32 v119, v119, v136
	v_exp_f32_e32 v163, v119
	v_cndmask_b32_e64 v119, v183, v187, s[28:29]
	v_cndmask_b32_e64 v181, v184, v188, s[30:31]
	s_waitcnt lgkmcnt(6)
	v_add_f32_e32 v119, v179, v119
	s_waitcnt lgkmcnt(5)
	v_add_f32_e32 v181, v214, v181
	v_exp_f32_e32 v179, v119
	v_exp_f32_e32 v191, v181
	v_cndmask_b32_e64 v181, v185, v189, s[34:35]
	s_waitcnt lgkmcnt(4)
	v_add_f32_e32 v181, v215, v181
	v_exp_f32_e32 v193, v181
	v_cndmask_b32_e64 v119, v163, 0, s[26:27]
	v_cndmask_b32_e64 v136, 0, v163, s[26:27]
	v_add_f32_e32 v162, 0, v162
	v_add_f32_e32 v163, 0, v163
	v_cndmask_b32_e64 v183, v191, 0, s[30:31]
	v_add_f32_e32 v162, v178, v162
	v_add_f32_e32 v163, v179, v163
	v_cndmask_b32_e64 v185, 0, v191, s[30:31]
	v_add_f32_e32 v162, v190, v162
	v_add_f32_e32 v163, v191, v163
	v_cndmask_b32_e64 v184, v193, 0, s[34:35]
	v_add_f32_e32 v162, v192, v162
	v_add_f32_e32 v163, v193, v163
	v_cndmask_b32_e64 v165, v179, 0, s[28:29]
	v_add_f32_e32 v124, v124, v162
	v_add_f32_e32 v125, v125, v163
	v_cndmask_b32_e64 v181, 0, v179, s[28:29]
	v_cndmask_b32_e64 v186, 0, v193, s[34:35]
	v_cvt_pk_bf16_f32 v182, v119, v165
	v_cvt_pk_bf16_f32 v183, v183, v184
	v_cvt_pk_bf16_f32 v184, v136, v181
	v_cvt_pk_bf16_f32 v185, v185, v186
	s_setprio 1
	s_waitcnt lgkmcnt(0)
	v_mfma_f32_16x16x32_bf16 v[12:15], v[174:177], v[182:185], v[12:15]
	v_mfma_f32_16x16x32_bf16 v[8:11], v[170:173], v[182:185], v[8:11]
	v_mfma_f32_16x16x32_bf16 v[4:7], v[166:169], v[182:185], v[4:7]
	v_mfma_f32_16x16x32_bf16 v[0:3], v[158:161], v[182:185], v[0:3]
	s_setprio 0

.LBB0_690:
	s_add_i32 s62, s40, -3
	s_cmp_ge_u32 s62, s38
	s_cselect_b64 s[52:53], -1, 0
	s_cmp_lt_u32 s62, s39
	s_cselect_b64 s[74:75], -1, 0
	s_and_b64 s[52:53], s[52:53], s[74:75]
	s_andn2_b64 vcc, exec, s[52:53]
	s_cbranch_vccnz .LBB0_692
	v_add_u32_e32 v178, v150, v149
	v_add_u32_e32 v181, 0x2000, v178
	v_add_u32_e32 v218, 0x2800, v178
	v_add_u32_e32 v219, 0x3000, v178
	v_add_u32_e32 v178, v150, v151
	v_add_u32_e32 v119, v148, v149
	v_add_u32_e32 v136, s60, v152
	v_add_u32_sdwa v163, s60, v144 dst_sel:DWORD dst_unused:UNUSED_PAD src0_sel:DWORD src1_sel:BYTE_2
	v_add_u32_sdwa v165, s60, v144 dst_sel:DWORD dst_unused:UNUSED_PAD src0_sel:DWORD src1_sel:BYTE_3
	v_add_u32_e32 v220, 0x2000, v178
	v_add_u32_sdwa v179, s60, v142 dst_sel:DWORD dst_unused:UNUSED_PAD src0_sel:DWORD src1_sel:BYTE_1
	ds_read_b128 v[158:161], v119
	ds_read_b128 v[166:169], v119 offset:64
	ds_read_b128 v[170:173], v119 offset:2304
	ds_read_b128 v[174:177], v119 offset:2368
	v_add_u32_e32 v162, s60, v153
	ds_read2_b64 v[182:185], v181 offset0:128 offset1:132
	ds_read2_b64 v[186:189], v218 offset0:160 offset1:164
	ds_read2_b64 v[190:193], v219 offset0:192 offset1:196
	ds_read2_b64 v[194:197], v220 offset0:128 offset1:132
	ds_read_b128 v[198:201], v119 offset:1152
	ds_read_b128 v[202:205], v119 offset:1216
	ds_read_b128 v[206:209], v119 offset:3456
	ds_read_b128 v[210:213], v119 offset:3520
	v_add_u32_e32 v178, s60, v155
	v_add_u32_sdwa v214, s60, v143 dst_sel:DWORD dst_unused:UNUSED_PAD src0_sel:DWORD src1_sel:BYTE_2
	v_add_u32_sdwa v215, s60, v143 dst_sel:DWORD dst_unused:UNUSED_PAD src0_sel:DWORD src1_sel:BYTE_3
	ds_read_b32 v136, v136 offset:41856
	ds_read_b32 v216, v162 offset:41856
	ds_read_b32 v163, v163 offset:41856
	ds_read_b32 v165, v165 offset:41856
	ds_read_b32 v217, v178 offset:41856
	ds_read_b32 v179, v179 offset:41856
	ds_read_b32 v221, v214 offset:41856
	ds_read_b32 v222, v215 offset:41856
	s_setprio 1
	s_waitcnt vmcnt(7) lgkmcnt(14)
	v_mfma_f32_16x16x32_bf16 v[158:161], v[158:161], v[80:83], 0
	s_waitcnt vmcnt(6)
	v_mfma_f32_16x16x32_bf16 v[158:161], v[166:169], v[84:87], v[158:161]
	v_mfma_f32_16x16x32_bf16 v[166:169], v[170:173], v[80:83], 0
	v_mfma_f32_16x16x32_bf16 v[166:169], v[174:177], v[84:87], v[166:169]
	s_setprio 0
	s_nop 6
	v_cndmask_b32_e64 v158, v166, v158, s[20:21]
	s_waitcnt lgkmcnt(7)
	v_add_f32_e32 v136, v136, v158
	v_exp_f32_e32 v162, v136
	v_cndmask_b32_e64 v136, v159, v167, s[10:11]
	v_cndmask_b32_e64 v159, v160, v168, s[12:13]
	s_waitcnt lgkmcnt(5)
	v_add_f32_e32 v159, v163, v159
	v_add_f32_e32 v136, v216, v136
	v_exp_f32_e32 v214, v159
	v_cndmask_b32_e64 v159, v161, v169, s[14:15]
	v_exp_f32_e32 v178, v136
	s_waitcnt lgkmcnt(4)
	v_add_f32_e32 v159, v165, v159
	v_exp_f32_e32 v216, v159
	v_cndmask_b32_e64 v159, v214, 0, s[12:13]
	v_cndmask_b32_e64 v158, v178, 0, s[10:11]
	v_cndmask_b32_e64 v160, 0, v178, s[10:11]
	v_cndmask_b32_e64 v161, 0, v214, s[12:13]
	v_cndmask_b32_e64 v136, 0, v162, s[20:21]
	v_cndmask_b32_e64 v166, v162, 0, s[20:21]
	v_cndmask_b32_e64 v163, v216, 0, s[14:15]
	v_cndmask_b32_e64 v165, 0, v216, s[14:15]
	v_cvt_pk_bf16_f32 v158, v136, v158
	v_cvt_pk_bf16_f32 v159, v159, v163
	v_cvt_pk_bf16_f32 v160, v166, v160
	v_cvt_pk_bf16_f32 v161, v161, v165
	s_setprio 1
	v_mfma_f32_16x16x32_bf16 v[60:63], v[182:185], v[158:161], v[60:63]
	v_mfma_f32_16x16x32_bf16 v[56:59], v[186:189], v[158:161], v[56:59]
	v_mfma_f32_16x16x32_bf16 v[52:55], v[190:193], v[158:161], v[52:55]
	v_mfma_f32_16x16x32_bf16 v[48:51], v[194:197], v[158:161], v[48:51]
	s_setprio 0
	ds_read2_b64 v[158:161], v181 offset0:130 offset1:134
	ds_read2_b64 v[166:169], v218 offset0:162 offset1:166
	ds_read2_b64 v[170:173], v219 offset0:194 offset1:198
	ds_read2_b64 v[174:177], v220 offset0:130 offset1:134
	ds_read_b128 v[182:185], v119 offset:3456
	ds_read_b128 v[186:189], v119 offset:3520
	ds_read_b128 v[190:193], v119 offset:5760
	ds_read_b128 v[194:197], v119 offset:5824
	v_add_u32_e32 v136, s60, v156
	v_add_u32_sdwa v165, s60, v141 dst_sel:DWORD dst_unused:UNUSED_PAD src0_sel:DWORD src1_sel:BYTE_2
	v_add_u32_sdwa v163, s60, v140 dst_sel:DWORD dst_unused:UNUSED_PAD src0_sel:DWORD src1_sel:BYTE_1
	v_add_u32_sdwa v215, s60, v141 dst_sel:DWORD dst_unused:UNUSED_PAD src0_sel:DWORD src1_sel:BYTE_3
	ds_read_b32 v136, v136 offset:41856
	ds_read_b32 v223, v163 offset:41856
	ds_read_b32 v165, v165 offset:41856
	ds_read_b32 v224, v215 offset:41856
	s_setprio 1
	s_waitcnt vmcnt(5)
	v_mfma_f32_16x16x32_bf16 v[198:201], v[198:201], v[88:91], 0
	s_waitcnt vmcnt(4)
	v_mfma_f32_16x16x32_bf16 v[198:201], v[202:205], v[92:95], v[198:201]
	v_mfma_f32_16x16x32_bf16 v[202:205], v[206:209], v[88:91], 0
	v_mfma_f32_16x16x32_bf16 v[202:205], v[210:213], v[92:95], v[202:205]
	s_setprio 0
	s_nop 6
	v_cndmask_b32_e64 v163, v198, v202, s[16:17]
	s_waitcnt lgkmcnt(14)
	v_add_f32_e32 v163, v217, v163
	v_cndmask_b32_e64 v198, v199, v203, s[18:19]
	v_cndmask_b32_e64 v200, v200, v204, s[6:7]
	v_exp_f32_e32 v163, v163
	v_add_f32_e32 v179, v179, v198
	s_waitcnt lgkmcnt(13)
	v_add_f32_e32 v200, v221, v200
	v_exp_f32_e32 v179, v179
	v_exp_f32_e32 v215, v200
	v_cndmask_b32_e64 v200, v201, v205, s[8:9]
	s_waitcnt lgkmcnt(12)
	v_add_f32_e32 v200, v222, v200
	v_exp_f32_e32 v217, v200
	v_cndmask_b32_e64 v198, v163, 0, s[16:17]
	v_cndmask_b32_e64 v202, 0, v163, s[16:17]
	v_add_f32_e32 v162, 0, v162
	v_add_f32_e32 v163, 0, v163
	v_cndmask_b32_e64 v199, v179, 0, s[18:19]
	v_add_f32_e32 v162, v178, v162
	v_add_f32_e32 v163, v179, v163
	v_cndmask_b32_e64 v200, 0, v179, s[18:19]
	v_add_f32_e32 v162, v214, v162
	v_add_f32_e32 v163, v215, v163
	v_cndmask_b32_e64 v201, v215, 0, s[6:7]
	v_add_f32_e32 v162, v216, v162
	v_add_f32_e32 v163, v217, v163
	v_cndmask_b32_e64 v203, 0, v215, s[6:7]
	v_add_f32_e32 v130, v130, v162
	v_add_f32_e32 v131, v131, v163
	v_cndmask_b32_e64 v204, v217, 0, s[8:9]
	v_cndmask_b32_e64 v205, 0, v217, s[8:9]
	v_cvt_pk_bf16_f32 v198, v198, v199
	v_cvt_pk_bf16_f32 v199, v201, v204
	v_cvt_pk_bf16_f32 v200, v202, v200
	v_cvt_pk_bf16_f32 v201, v203, v205
	s_setprio 1
	s_waitcnt lgkmcnt(11)
	v_mfma_f32_16x16x32_bf16 v[44:47], v[158:161], v[198:201], v[44:47]
	s_waitcnt lgkmcnt(10)
	v_mfma_f32_16x16x32_bf16 v[40:43], v[166:169], v[198:201], v[40:43]
	s_waitcnt lgkmcnt(9)
	v_mfma_f32_16x16x32_bf16 v[36:39], v[170:173], v[198:201], v[36:39]
	s_waitcnt lgkmcnt(8)
	v_mfma_f32_16x16x32_bf16 v[32:35], v[174:177], v[198:201], v[32:35]
	s_setprio 0
	ds_read2_b64 v[158:161], v181 offset0:134 offset1:138
	ds_read2_b64 v[166:169], v218 offset0:166 offset1:170
	ds_read2_b64 v[170:173], v219 offset0:198 offset1:202
	ds_read2_b64 v[174:177], v220 offset0:134 offset1:138
	ds_read_b128 v[198:201], v119 offset:4608
	ds_read_b128 v[202:205], v119 offset:4672
	v_add_u32_e32 v119, v148, v151
	ds_read_b128 v[206:209], v119
	ds_read_b128 v[210:213], v119 offset:64
	v_add_u32_e32 v119, s60, v154
	v_add_u32_sdwa v162, s60, v145 dst_sel:DWORD dst_unused:UNUSED_PAD src0_sel:DWORD src1_sel:BYTE_1
	v_add_u32_sdwa v163, s60, v146 dst_sel:DWORD dst_unused:UNUSED_PAD src0_sel:DWORD src1_sel:BYTE_2
	v_add_u32_sdwa v178, s60, v146 dst_sel:DWORD dst_unused:UNUSED_PAD src0_sel:DWORD src1_sel:BYTE_3
	ds_read_b32 v119, v119 offset:41856
	ds_read_b32 v179, v162 offset:41856
	ds_read_b32 v214, v163 offset:41856
	ds_read_b32 v215, v178 offset:41856
	s_setprio 1
	s_waitcnt vmcnt(3) lgkmcnt(14)
	v_mfma_f32_16x16x32_bf16 v[182:185], v[182:185], v[96:99], 0
	s_waitcnt vmcnt(2)
	v_mfma_f32_16x16x32_bf16 v[182:185], v[186:189], v[100:103], v[182:185]
	v_mfma_f32_16x16x32_bf16 v[186:189], v[190:193], v[96:99], 0
	v_mfma_f32_16x16x32_bf16 v[186:189], v[194:197], v[100:103], v[186:189]
	s_setprio 0
	s_nop 6
	v_cndmask_b32_e64 v162, v186, v182, s[2:3]
	v_add_f32_e32 v136, v136, v162
	v_exp_f32_e32 v162, v136
	v_cndmask_b32_e64 v136, v187, v183, s[4:5]
	v_cndmask_b32_e64 v183, v184, v188, s[22:23]
	s_waitcnt lgkmcnt(13)
	v_add_f32_e32 v165, v165, v183
	v_exp_f32_e32 v190, v165
	v_cndmask_b32_e64 v165, v185, v189, s[24:25]
	v_add_f32_e32 v136, v223, v136
	s_waitcnt lgkmcnt(12)
	v_add_f32_e32 v165, v224, v165
	v_exp_f32_e32 v178, v136
	v_exp_f32_e32 v192, v165
	v_cndmask_b32_e64 v183, v190, 0, s[22:23]
	v_cndmask_b32_e64 v185, 0, v190, s[22:23]
	v_cndmask_b32_e64 v182, 0, v178, s[4:5]
	v_cndmask_b32_e64 v184, v192, 0, s[24:25]
	v_cndmask_b32_e64 v136, 0, v162, s[2:3]
	v_cndmask_b32_e64 v163, v162, 0, s[2:3]
	v_cndmask_b32_e64 v165, v178, 0, s[4:5]
	v_cndmask_b32_e64 v186, 0, v192, s[24:25]
	v_cvt_pk_bf16_f32 v182, v136, v182
	v_cvt_pk_bf16_f32 v183, v183, v184
	v_cvt_pk_bf16_f32 v184, v163, v165
	v_cvt_pk_bf16_f32 v185, v185, v186
	s_setprio 1
	s_waitcnt lgkmcnt(11)
	v_mfma_f32_16x16x32_bf16 v[28:31], v[158:161], v[182:185], v[28:31]
	s_waitcnt lgkmcnt(10)
	v_mfma_f32_16x16x32_bf16 v[24:27], v[166:169], v[182:185], v[24:27]
	s_waitcnt lgkmcnt(9)
	v_mfma_f32_16x16x32_bf16 v[20:23], v[170:173], v[182:185], v[20:23]
	s_waitcnt lgkmcnt(8)
	v_mfma_f32_16x16x32_bf16 v[16:19], v[174:177], v[182:185], v[16:19]
	s_setprio 0
	ds_read2_b64 v[158:161], v220 offset0:136 offset1:140
	ds_read2_b64 v[166:169], v219 offset0:200 offset1:204
	ds_read2_b64 v[170:173], v218 offset0:168 offset1:172
	ds_read2_b64 v[174:177], v181 offset0:136 offset1:140
	s_setprio 1
	s_waitcnt vmcnt(1) lgkmcnt(11)
	v_mfma_f32_16x16x32_bf16 v[182:185], v[198:201], v[104:107], 0
	s_waitcnt lgkmcnt(9)
	v_mfma_f32_16x16x32_bf16 v[186:189], v[206:209], v[104:107], 0
	s_waitcnt vmcnt(0)
	v_mfma_f32_16x16x32_bf16 v[182:185], v[202:205], v[108:111], v[182:185]
	s_waitcnt lgkmcnt(8)
	v_mfma_f32_16x16x32_bf16 v[186:189], v[210:213], v[108:111], v[186:189]
	s_setprio 0
	s_nop 6
	v_cndmask_b32_e64 v136, v182, v186, s[26:27]
	s_waitcnt lgkmcnt(7)
	v_add_f32_e32 v119, v119, v136
	v_exp_f32_e32 v163, v119
	v_cndmask_b32_e64 v119, v183, v187, s[28:29]
	v_cndmask_b32_e64 v181, v184, v188, s[30:31]
	s_waitcnt lgkmcnt(6)
	v_add_f32_e32 v119, v179, v119
	s_waitcnt lgkmcnt(5)
	v_add_f32_e32 v181, v214, v181
	v_exp_f32_e32 v179, v119
	v_exp_f32_e32 v191, v181
	v_cndmask_b32_e64 v181, v185, v189, s[34:35]
	s_waitcnt lgkmcnt(4)
	v_add_f32_e32 v181, v215, v181
	v_exp_f32_e32 v193, v181
	v_cndmask_b32_e64 v119, v163, 0, s[26:27]
	v_cndmask_b32_e64 v136, 0, v163, s[26:27]
	v_add_f32_e32 v162, 0, v162
	v_add_f32_e32 v163, 0, v163
	v_cndmask_b32_e64 v183, v191, 0, s[30:31]
	v_add_f32_e32 v162, v178, v162
	v_add_f32_e32 v163, v179, v163
	v_cndmask_b32_e64 v185, 0, v191, s[30:31]
	v_add_f32_e32 v162, v190, v162
	v_add_f32_e32 v163, v191, v163
	v_cndmask_b32_e64 v184, v193, 0, s[34:35]
	v_add_f32_e32 v162, v192, v162
	v_add_f32_e32 v163, v193, v163
	v_cndmask_b32_e64 v165, v179, 0, s[28:29]
	v_add_f32_e32 v124, v124, v162
	v_add_f32_e32 v125, v125, v163
	v_cndmask_b32_e64 v181, 0, v179, s[28:29]
	v_cndmask_b32_e64 v186, 0, v193, s[34:35]
	v_cvt_pk_bf16_f32 v182, v119, v165
	v_cvt_pk_bf16_f32 v183, v183, v184
	v_cvt_pk_bf16_f32 v184, v136, v181
	v_cvt_pk_bf16_f32 v185, v185, v186
	s_setprio 1
	s_waitcnt lgkmcnt(0)
	v_mfma_f32_16x16x32_bf16 v[12:15], v[174:177], v[182:185], v[12:15]
	v_mfma_f32_16x16x32_bf16 v[8:11], v[170:173], v[182:185], v[8:11]
	v_mfma_f32_16x16x32_bf16 v[4:7], v[166:169], v[182:185], v[4:7]
	v_mfma_f32_16x16x32_bf16 v[0:3], v[158:161], v[182:185], v[0:3]
	s_setprio 0

.LBB0_697:
	s_add_i32 s52, s40, -2
	s_cmp_ge_u32 s52, s38
	s_cselect_b64 s[62:63], -1, 0
	s_cmp_lt_u32 s52, s39
	s_cselect_b64 s[74:75], -1, 0
	s_and_b64 s[62:63], s[62:63], s[74:75]
	s_andn2_b64 vcc, exec, s[62:63]
	s_cbranch_vccnz .LBB0_699
	v_add_u32_e32 v178, v150, v149
	v_add_u32_e32 v181, 0x6800, v178
	v_add_u32_e32 v218, 0x7000, v178
	v_add_u32_e32 v219, 0x7800, v178
	v_add_u32_e32 v178, v150, v151
	v_add_u32_e32 v119, v148, v149
	v_add_u32_e32 v136, s60, v152
	v_add_u32_sdwa v163, s60, v144 dst_sel:DWORD dst_unused:UNUSED_PAD src0_sel:DWORD src1_sel:BYTE_2
	v_add_u32_sdwa v165, s60, v144 dst_sel:DWORD dst_unused:UNUSED_PAD src0_sel:DWORD src1_sel:BYTE_3
	v_add_u32_e32 v220, 0x6800, v178
	v_add_u32_sdwa v179, s60, v142 dst_sel:DWORD dst_unused:UNUSED_PAD src0_sel:DWORD src1_sel:BYTE_1
	ds_read_b128 v[158:161], v119 offset:18432
	ds_read_b128 v[166:169], v119 offset:18496
	ds_read_b128 v[170:173], v119 offset:20736
	ds_read_b128 v[174:177], v119 offset:20800
	v_add_u32_e32 v162, s60, v153
	ds_read2_b64 v[182:185], v181 offset0:128 offset1:132
	ds_read2_b64 v[186:189], v218 offset0:160 offset1:164
	ds_read2_b64 v[190:193], v219 offset0:192 offset1:196
	ds_read2_b64 v[194:197], v220 offset0:128 offset1:132
	ds_read_b128 v[198:201], v119 offset:19584
	ds_read_b128 v[202:205], v119 offset:19648
	ds_read_b128 v[206:209], v119 offset:21888
	ds_read_b128 v[210:213], v119 offset:21952
	v_add_u32_e32 v178, s60, v155
	v_add_u32_sdwa v214, s60, v143 dst_sel:DWORD dst_unused:UNUSED_PAD src0_sel:DWORD src1_sel:BYTE_2
	v_add_u32_sdwa v215, s60, v143 dst_sel:DWORD dst_unused:UNUSED_PAD src0_sel:DWORD src1_sel:BYTE_3
	ds_read_b32 v136, v136 offset:41984
	ds_read_b32 v216, v162 offset:41984
	ds_read_b32 v163, v163 offset:41984
	ds_read_b32 v165, v165 offset:41984
	ds_read_b32 v217, v178 offset:41984
	ds_read_b32 v179, v179 offset:41984
	ds_read_b32 v221, v214 offset:41984
	ds_read_b32 v222, v215 offset:41984
	s_setprio 1
	s_waitcnt vmcnt(7) lgkmcnt(14)
	v_mfma_f32_16x16x32_bf16 v[158:161], v[158:161], v[80:83], 0
	s_waitcnt vmcnt(6)
	v_mfma_f32_16x16x32_bf16 v[158:161], v[166:169], v[84:87], v[158:161]
	v_mfma_f32_16x16x32_bf16 v[166:169], v[170:173], v[80:83], 0
	v_mfma_f32_16x16x32_bf16 v[166:169], v[174:177], v[84:87], v[166:169]
	s_setprio 0
	s_nop 6
	v_cndmask_b32_e64 v158, v166, v158, s[20:21]
	s_waitcnt lgkmcnt(7)
	v_add_f32_e32 v136, v136, v158
	v_exp_f32_e32 v162, v136
	v_cndmask_b32_e64 v136, v159, v167, s[10:11]
	v_cndmask_b32_e64 v159, v160, v168, s[12:13]
	s_waitcnt lgkmcnt(5)
	v_add_f32_e32 v159, v163, v159
	v_add_f32_e32 v136, v216, v136
	v_exp_f32_e32 v214, v159
	v_cndmask_b32_e64 v159, v161, v169, s[14:15]
	v_exp_f32_e32 v178, v136
	s_waitcnt lgkmcnt(4)
	v_add_f32_e32 v159, v165, v159
	v_exp_f32_e32 v216, v159
	v_cndmask_b32_e64 v159, v214, 0, s[12:13]
	v_cndmask_b32_e64 v158, v178, 0, s[10:11]
	v_cndmask_b32_e64 v160, 0, v178, s[10:11]
	v_cndmask_b32_e64 v161, 0, v214, s[12:13]
	v_cndmask_b32_e64 v136, 0, v162, s[20:21]
	v_cndmask_b32_e64 v166, v162, 0, s[20:21]
	v_cndmask_b32_e64 v163, v216, 0, s[14:15]
	v_cndmask_b32_e64 v165, 0, v216, s[14:15]
	v_cvt_pk_bf16_f32 v158, v136, v158
	v_cvt_pk_bf16_f32 v159, v159, v163
	v_cvt_pk_bf16_f32 v160, v166, v160
	v_cvt_pk_bf16_f32 v161, v161, v165
	s_setprio 1
	v_mfma_f32_16x16x32_bf16 v[60:63], v[182:185], v[158:161], v[60:63]
	v_mfma_f32_16x16x32_bf16 v[56:59], v[186:189], v[158:161], v[56:59]
	v_mfma_f32_16x16x32_bf16 v[52:55], v[190:193], v[158:161], v[52:55]
	v_mfma_f32_16x16x32_bf16 v[48:51], v[194:197], v[158:161], v[48:51]
	s_setprio 0
	ds_read2_b64 v[158:161], v181 offset0:130 offset1:134
	ds_read2_b64 v[166:169], v218 offset0:162 offset1:166
	ds_read2_b64 v[170:173], v219 offset0:194 offset1:198
	ds_read2_b64 v[174:177], v220 offset0:130 offset1:134
	ds_read_b128 v[182:185], v119 offset:21888
	ds_read_b128 v[186:189], v119 offset:21952
	ds_read_b128 v[190:193], v119 offset:24192
	ds_read_b128 v[194:197], v119 offset:24256
	v_add_u32_e32 v136, s60, v156
	v_add_u32_sdwa v165, s60, v141 dst_sel:DWORD dst_unused:UNUSED_PAD src0_sel:DWORD src1_sel:BYTE_2
	v_add_u32_sdwa v163, s60, v140 dst_sel:DWORD dst_unused:UNUSED_PAD src0_sel:DWORD src1_sel:BYTE_1
	v_add_u32_sdwa v215, s60, v141 dst_sel:DWORD dst_unused:UNUSED_PAD src0_sel:DWORD src1_sel:BYTE_3
	ds_read_b32 v136, v136 offset:41984
	ds_read_b32 v223, v163 offset:41984
	ds_read_b32 v165, v165 offset:41984
	ds_read_b32 v224, v215 offset:41984
	s_setprio 1
	s_waitcnt vmcnt(5)
	v_mfma_f32_16x16x32_bf16 v[198:201], v[198:201], v[88:91], 0
	s_waitcnt vmcnt(4)
	v_mfma_f32_16x16x32_bf16 v[198:201], v[202:205], v[92:95], v[198:201]
	v_mfma_f32_16x16x32_bf16 v[202:205], v[206:209], v[88:91], 0
	v_mfma_f32_16x16x32_bf16 v[202:205], v[210:213], v[92:95], v[202:205]
	s_setprio 0
	s_nop 6
	v_cndmask_b32_e64 v163, v198, v202, s[16:17]
	s_waitcnt lgkmcnt(14)
	v_add_f32_e32 v163, v217, v163
	v_cndmask_b32_e64 v198, v199, v203, s[18:19]
	v_cndmask_b32_e64 v200, v200, v204, s[6:7]
	v_exp_f32_e32 v163, v163
	v_add_f32_e32 v179, v179, v198
	s_waitcnt lgkmcnt(13)
	v_add_f32_e32 v200, v221, v200
	v_exp_f32_e32 v179, v179
	v_exp_f32_e32 v215, v200
	v_cndmask_b32_e64 v200, v201, v205, s[8:9]
	s_waitcnt lgkmcnt(12)
	v_add_f32_e32 v200, v222, v200
	v_exp_f32_e32 v217, v200
	v_cndmask_b32_e64 v198, v163, 0, s[16:17]
	v_cndmask_b32_e64 v202, 0, v163, s[16:17]
	v_add_f32_e32 v162, 0, v162
	v_add_f32_e32 v163, 0, v163
	v_cndmask_b32_e64 v199, v179, 0, s[18:19]
	v_add_f32_e32 v162, v178, v162
	v_add_f32_e32 v163, v179, v163
	v_cndmask_b32_e64 v200, 0, v179, s[18:19]
	v_add_f32_e32 v162, v214, v162
	v_add_f32_e32 v163, v215, v163
	v_cndmask_b32_e64 v201, v215, 0, s[6:7]
	v_add_f32_e32 v162, v216, v162
	v_add_f32_e32 v163, v217, v163
	v_cndmask_b32_e64 v203, 0, v215, s[6:7]
	v_add_f32_e32 v130, v130, v162
	v_add_f32_e32 v131, v131, v163
	v_cndmask_b32_e64 v204, v217, 0, s[8:9]
	v_cndmask_b32_e64 v205, 0, v217, s[8:9]
	v_cvt_pk_bf16_f32 v198, v198, v199
	v_cvt_pk_bf16_f32 v199, v201, v204
	v_cvt_pk_bf16_f32 v200, v202, v200
	v_cvt_pk_bf16_f32 v201, v203, v205
	s_setprio 1
	s_waitcnt lgkmcnt(11)
	v_mfma_f32_16x16x32_bf16 v[44:47], v[158:161], v[198:201], v[44:47]
	s_waitcnt lgkmcnt(10)
	v_mfma_f32_16x16x32_bf16 v[40:43], v[166:169], v[198:201], v[40:43]
	s_waitcnt lgkmcnt(9)
	v_mfma_f32_16x16x32_bf16 v[36:39], v[170:173], v[198:201], v[36:39]
	s_waitcnt lgkmcnt(8)
	v_mfma_f32_16x16x32_bf16 v[32:35], v[174:177], v[198:201], v[32:35]
	s_setprio 0
	ds_read2_b64 v[158:161], v181 offset0:134 offset1:138
	ds_read2_b64 v[166:169], v218 offset0:166 offset1:170
	ds_read2_b64 v[170:173], v219 offset0:198 offset1:202
	ds_read2_b64 v[174:177], v220 offset0:134 offset1:138
	ds_read_b128 v[198:201], v119 offset:23040
	ds_read_b128 v[202:205], v119 offset:23104
	v_add_u32_e32 v119, v148, v151
	ds_read_b128 v[206:209], v119 offset:18432
	ds_read_b128 v[210:213], v119 offset:18496
	v_add_u32_e32 v119, s60, v154
	v_add_u32_sdwa v162, s60, v145 dst_sel:DWORD dst_unused:UNUSED_PAD src0_sel:DWORD src1_sel:BYTE_1
	v_add_u32_sdwa v163, s60, v146 dst_sel:DWORD dst_unused:UNUSED_PAD src0_sel:DWORD src1_sel:BYTE_2
	v_add_u32_sdwa v178, s60, v146 dst_sel:DWORD dst_unused:UNUSED_PAD src0_sel:DWORD src1_sel:BYTE_3
	ds_read_b32 v119, v119 offset:41984
	ds_read_b32 v179, v162 offset:41984
	ds_read_b32 v214, v163 offset:41984
	ds_read_b32 v215, v178 offset:41984
	s_setprio 1
	s_waitcnt vmcnt(3) lgkmcnt(14)
	v_mfma_f32_16x16x32_bf16 v[182:185], v[182:185], v[96:99], 0
	s_waitcnt vmcnt(2)
	v_mfma_f32_16x16x32_bf16 v[182:185], v[186:189], v[100:103], v[182:185]
	v_mfma_f32_16x16x32_bf16 v[186:189], v[190:193], v[96:99], 0
	v_mfma_f32_16x16x32_bf16 v[186:189], v[194:197], v[100:103], v[186:189]
	s_setprio 0
	s_nop 6
	v_cndmask_b32_e64 v162, v186, v182, s[2:3]
	v_add_f32_e32 v136, v136, v162
	v_exp_f32_e32 v162, v136
	v_cndmask_b32_e64 v136, v187, v183, s[4:5]
	v_cndmask_b32_e64 v183, v184, v188, s[22:23]
	s_waitcnt lgkmcnt(13)
	v_add_f32_e32 v165, v165, v183
	v_exp_f32_e32 v190, v165
	v_cndmask_b32_e64 v165, v185, v189, s[24:25]
	v_add_f32_e32 v136, v223, v136
	s_waitcnt lgkmcnt(12)
	v_add_f32_e32 v165, v224, v165
	v_exp_f32_e32 v178, v136
	v_exp_f32_e32 v192, v165
	v_cndmask_b32_e64 v183, v190, 0, s[22:23]
	v_cndmask_b32_e64 v185, 0, v190, s[22:23]
	v_cndmask_b32_e64 v182, 0, v178, s[4:5]
	v_cndmask_b32_e64 v184, v192, 0, s[24:25]
	v_cndmask_b32_e64 v136, 0, v162, s[2:3]
	v_cndmask_b32_e64 v163, v162, 0, s[2:3]
	v_cndmask_b32_e64 v165, v178, 0, s[4:5]
	v_cndmask_b32_e64 v186, 0, v192, s[24:25]
	v_cvt_pk_bf16_f32 v182, v136, v182
	v_cvt_pk_bf16_f32 v183, v183, v184
	v_cvt_pk_bf16_f32 v184, v163, v165
	v_cvt_pk_bf16_f32 v185, v185, v186
	s_setprio 1
	s_waitcnt lgkmcnt(11)
	v_mfma_f32_16x16x32_bf16 v[28:31], v[158:161], v[182:185], v[28:31]
	s_waitcnt lgkmcnt(10)
	v_mfma_f32_16x16x32_bf16 v[24:27], v[166:169], v[182:185], v[24:27]
	s_waitcnt lgkmcnt(9)
	v_mfma_f32_16x16x32_bf16 v[20:23], v[170:173], v[182:185], v[20:23]
	s_waitcnt lgkmcnt(8)
	v_mfma_f32_16x16x32_bf16 v[16:19], v[174:177], v[182:185], v[16:19]
	s_setprio 0
	ds_read2_b64 v[158:161], v220 offset0:136 offset1:140
	ds_read2_b64 v[166:169], v219 offset0:200 offset1:204
	ds_read2_b64 v[170:173], v218 offset0:168 offset1:172
	ds_read2_b64 v[174:177], v181 offset0:136 offset1:140
	s_setprio 1
	s_waitcnt vmcnt(1) lgkmcnt(11)
	v_mfma_f32_16x16x32_bf16 v[182:185], v[198:201], v[104:107], 0
	s_waitcnt lgkmcnt(9)
	v_mfma_f32_16x16x32_bf16 v[186:189], v[206:209], v[104:107], 0
	s_waitcnt vmcnt(0)
	v_mfma_f32_16x16x32_bf16 v[182:185], v[202:205], v[108:111], v[182:185]
	s_waitcnt lgkmcnt(8)
	v_mfma_f32_16x16x32_bf16 v[186:189], v[210:213], v[108:111], v[186:189]
	s_setprio 0
	s_nop 6
	v_cndmask_b32_e64 v136, v182, v186, s[26:27]
	s_waitcnt lgkmcnt(7)
	v_add_f32_e32 v119, v119, v136
	v_exp_f32_e32 v163, v119
	v_cndmask_b32_e64 v119, v183, v187, s[28:29]
	v_cndmask_b32_e64 v181, v184, v188, s[30:31]
	s_waitcnt lgkmcnt(6)
	v_add_f32_e32 v119, v179, v119
	s_waitcnt lgkmcnt(5)
	v_add_f32_e32 v181, v214, v181
	v_exp_f32_e32 v179, v119
	v_exp_f32_e32 v191, v181
	v_cndmask_b32_e64 v181, v185, v189, s[34:35]
	s_waitcnt lgkmcnt(4)
	v_add_f32_e32 v181, v215, v181
	v_exp_f32_e32 v193, v181
	v_cndmask_b32_e64 v119, v163, 0, s[26:27]
	v_cndmask_b32_e64 v136, 0, v163, s[26:27]
	v_add_f32_e32 v162, 0, v162
	v_add_f32_e32 v163, 0, v163
	v_cndmask_b32_e64 v183, v191, 0, s[30:31]
	v_add_f32_e32 v162, v178, v162
	v_add_f32_e32 v163, v179, v163
	v_cndmask_b32_e64 v185, 0, v191, s[30:31]
	v_add_f32_e32 v162, v190, v162
	v_add_f32_e32 v163, v191, v163
	v_cndmask_b32_e64 v184, v193, 0, s[34:35]
	v_add_f32_e32 v162, v192, v162
	v_add_f32_e32 v163, v193, v163
	v_cndmask_b32_e64 v165, v179, 0, s[28:29]
	v_add_f32_e32 v124, v124, v162
	v_add_f32_e32 v125, v125, v163
	v_cndmask_b32_e64 v181, 0, v179, s[28:29]
	v_cndmask_b32_e64 v186, 0, v193, s[34:35]
	v_cvt_pk_bf16_f32 v182, v119, v165
	v_cvt_pk_bf16_f32 v183, v183, v184
	v_cvt_pk_bf16_f32 v184, v136, v181
	v_cvt_pk_bf16_f32 v185, v185, v186
	s_setprio 1
	s_waitcnt lgkmcnt(0)
	v_mfma_f32_16x16x32_bf16 v[12:15], v[174:177], v[182:185], v[12:15]
	v_mfma_f32_16x16x32_bf16 v[8:11], v[170:173], v[182:185], v[8:11]
	v_mfma_f32_16x16x32_bf16 v[4:7], v[166:169], v[182:185], v[4:7]
	v_mfma_f32_16x16x32_bf16 v[0:3], v[158:161], v[182:185], v[0:3]
	s_setprio 0

.LBB0_760:
	s_or_b64 exec, exec, s[6:7]
	s_mov_b64 s[6:7], exec
	v_mbcnt_lo_u32_b32 v0, s6, 0
	v_mbcnt_hi_u32_b32 v0, s7, v0
	v_cmp_eq_u32_e32 vcc, 0, v0
	s_waitcnt vmcnt(0)
	buffer_inv sc1
	s_and_saveexec_b64 s[8:9], vcc
	s_cbranch_execz .LBB0_762
	s_bcnt1_i32_b64 s6, s[6:7]
	v_mov_b32_e32 v0, 0x2000
	v_mov_b32_e32 v1, s6
.LBB0_762:
	s_or_b64 exec, exec, s[8:9]
	s_waitcnt vmcnt(0)

.LBB0_764:
	s_cmp_lt_i32 s82, 6
	s_cselect_b64 s[2:3], -1, 0
	s_and_b64 s[8:9], s[2:3], s[0:1]
	s_andn2_b64 vcc, exec, s[8:9]
	s_cbranch_vccnz .LBB0_832
	s_ashr_i32 s46, s84, 31
	s_ashr_i32 s47, s33, 31
	s_cmpk_lt_i32 s33, 0x500
	s_cselect_b64 s[10:11], -1, 0
	s_cmpk_gt_i32 s33, 0x4ff
	s_cbranch_scc1 .LBB0_786
	s_cmp_eq_u32 s84, 0x100
	s_cbranch_scc0 .Lp5rs_orig
	s_and_b32 s0, s33, 7
	s_mul_i32 s0, s0, 40
	s_lshr_b32 s1, s33, 7
	s_lshl_b32 s1, s1, 2
	s_add_i32 s0, s0, s1
	s_bfe_u32 s1, s33, 0x20003
	s_add_i32 s0, s0, s1
	s_lshl_b32 s0, s0, 10
	v_cmp_gt_u32_e32 vcc, 0x100, v164
	s_and_saveexec_b64 s[4:5], vcc
	v_lshl_add_u32 v11, v164, 2, s0
	s_add_u32 s12, s80, 0xa0000
	s_addc_u32 s13, s81, 0
	s_add_u32 s14, s80, 0x50000
	s_addc_u32 s15, s81, 0
	s_waitcnt lgkmcnt(0)
	global_load_dword v16, v11, s[14:15]
	global_load_dword v17, v11, s[12:13]
	v_add_u32_e32 v12, 0x2000, v11
	global_load_dword v18, v12, s[14:15]
	global_load_dword v19, v12, s[12:13]
	v_add_u32_e32 v13, 0x4000, v11
	global_load_dword v20, v13, s[14:15]
	global_load_dword v21, v13, s[12:13]
	v_add_u32_e32 v14, 0x6000, v11
	global_load_dword v22, v14, s[14:15]
	global_load_dword v23, v14, s[12:13]
	v_add_u32_e32 v15, 0x8000, v11
	global_load_dword v24, v15, s[14:15]
	global_load_dword v25, v15, s[12:13]
	v_lshlrev_b32_e32 v0, 3, v164
	s_waitcnt vmcnt(8)
	v_mov_b32_e32 v1, v16
	v_mov_b32_e32 v6, v17
	v_mov_b32_e32 v2, 0x358637bd
	s_mov_b32 s7, 0x800000
	s_mov_b32 s6, 0xf800000
	v_mov_b32_e32 v3, 0x260
	v_fmamk_f32 v1, v1, 0x3b000000, v2
	v_fmac_f32_e32 v2, 0x3b000000, v6
	v_div_scale_f32 v4, s[0:1], v2, v2, v1
	v_rcp_f32_e32 v7, v4
	v_div_scale_f32 v5, vcc, v1, v2, v1
	v_mul_f32_e32 v6, 0x4b800000, v1
	v_fma_f32 v8, -v4, v7, 1.0
	v_fmac_f32_e32 v7, v8, v7
	v_mul_f32_e32 v8, v5, v7
	v_fma_f32 v9, -v4, v8, v5
	v_fmac_f32_e32 v8, v9, v7
	v_fma_f32 v4, -v4, v8, v5
	v_cmp_gt_f32_e64 s[0:1], s7, v1
	v_div_fmas_f32 v4, v4, v7, v8
	s_nop 0
	v_cndmask_b32_e64 v6, v1, v6, s[0:1]
	v_div_fixup_f32 v1, v4, v2, v1
	v_mul_f32_e32 v2, 0x4f800000, v1
	v_cmp_gt_f32_e32 vcc, s6, v1
	v_rsq_f32_e32 v6, v6
	v_add_u32_e32 v4, 0, v0
	v_cndmask_b32_e32 v1, v1, v2, vcc
	v_sqrt_f32_e32 v2, v1
	v_mul_f32_e32 v5, 0x45800000, v6
	v_add_u32_e32 v4, 0x20400, v4
	v_add_u32_e32 v7, -1, v2
	v_add_u32_e32 v8, 1, v2
	v_fma_f32 v9, -v7, v2, v1
	v_fma_f32 v10, -v8, v2, v1
	v_cmp_ge_f32_e64 s[6:7], 0, v9
	s_nop 1
	v_cndmask_b32_e64 v2, v2, v7, s[6:7]
	v_cmp_lt_f32_e64 s[6:7], 0, v10
	s_nop 1
	v_cndmask_b32_e64 v2, v2, v8, s[6:7]
	v_mul_f32_e32 v7, 0x37800000, v2
	v_cndmask_b32_e32 v2, v2, v7, vcc
	v_cmp_class_f32_e32 vcc, v1, v3
	v_cndmask_b32_e64 v3, v6, v5, s[0:1]
	s_nop 0
	v_cndmask_b32_e32 v2, v2, v1, vcc
	ds_write_b64 v4, v[2:3]
	s_waitcnt vmcnt(6)
	v_mov_b32_e32 v1, v18
	v_mov_b32_e32 v6, v19
	v_mov_b32_e32 v2, 0x358637bd
	s_mov_b32 s7, 0x800000
	s_mov_b32 s6, 0xf800000
	v_mov_b32_e32 v3, 0x260
	v_fmamk_f32 v1, v1, 0x3b000000, v2
	v_fmac_f32_e32 v2, 0x3b000000, v6
	v_div_scale_f32 v4, s[0:1], v2, v2, v1
	v_rcp_f32_e32 v7, v4
	v_div_scale_f32 v5, vcc, v1, v2, v1
	v_mul_f32_e32 v6, 0x4b800000, v1
	v_fma_f32 v8, -v4, v7, 1.0
	v_fmac_f32_e32 v7, v8, v7
	v_mul_f32_e32 v8, v5, v7
	v_fma_f32 v9, -v4, v8, v5
	v_fmac_f32_e32 v8, v9, v7
	v_fma_f32 v4, -v4, v8, v5
	v_cmp_gt_f32_e64 s[0:1], s7, v1
	v_div_fmas_f32 v4, v4, v7, v8
	s_nop 0
	v_cndmask_b32_e64 v6, v1, v6, s[0:1]
	v_div_fixup_f32 v1, v4, v2, v1
	v_mul_f32_e32 v2, 0x4f800000, v1
	v_cmp_gt_f32_e32 vcc, s6, v1
	v_rsq_f32_e32 v6, v6
	v_add_u32_e32 v4, 0, v0
	v_cndmask_b32_e32 v1, v1, v2, vcc
	v_sqrt_f32_e32 v2, v1
	v_mul_f32_e32 v5, 0x45800000, v6
	v_add_u32_e32 v4, 0x20400, v4
	v_add_u32_e32 v7, -1, v2
	v_add_u32_e32 v8, 1, v2
	v_fma_f32 v9, -v7, v2, v1
	v_fma_f32 v10, -v8, v2, v1
	v_cmp_ge_f32_e64 s[6:7], 0, v9
	s_nop 1
	v_cndmask_b32_e64 v2, v2, v7, s[6:7]
	v_cmp_lt_f32_e64 s[6:7], 0, v10
	s_nop 1
	v_cndmask_b32_e64 v2, v2, v8, s[6:7]
	v_mul_f32_e32 v7, 0x37800000, v2
	v_cndmask_b32_e32 v2, v2, v7, vcc
	v_cmp_class_f32_e32 vcc, v1, v3
	v_cndmask_b32_e64 v3, v6, v5, s[0:1]
	s_nop 0
	v_cndmask_b32_e32 v2, v2, v1, vcc
	ds_write_b64 v4, v[2:3] offset:2048
	s_waitcnt vmcnt(4)
	v_mov_b32_e32 v1, v20
	v_mov_b32_e32 v6, v21
	v_mov_b32_e32 v2, 0x358637bd
	s_mov_b32 s7, 0x800000
	s_mov_b32 s6, 0xf800000
	v_mov_b32_e32 v3, 0x260
	v_fmamk_f32 v1, v1, 0x3b000000, v2
	v_fmac_f32_e32 v2, 0x3b000000, v6
	v_div_scale_f32 v4, s[0:1], v2, v2, v1
	v_rcp_f32_e32 v7, v4
	v_div_scale_f32 v5, vcc, v1, v2, v1
	v_mul_f32_e32 v6, 0x4b800000, v1
	v_fma_f32 v8, -v4, v7, 1.0
	v_fmac_f32_e32 v7, v8, v7
	v_mul_f32_e32 v8, v5, v7
	v_fma_f32 v9, -v4, v8, v5
	v_fmac_f32_e32 v8, v9, v7
	v_fma_f32 v4, -v4, v8, v5
	v_cmp_gt_f32_e64 s[0:1], s7, v1
	v_div_fmas_f32 v4, v4, v7, v8
	s_nop 0
	v_cndmask_b32_e64 v6, v1, v6, s[0:1]
	v_div_fixup_f32 v1, v4, v2, v1
	v_mul_f32_e32 v2, 0x4f800000, v1
	v_cmp_gt_f32_e32 vcc, s6, v1
	v_rsq_f32_e32 v6, v6
	v_add_u32_e32 v4, 0, v0
	v_cndmask_b32_e32 v1, v1, v2, vcc
	v_sqrt_f32_e32 v2, v1
	v_mul_f32_e32 v5, 0x45800000, v6
	v_add_u32_e32 v4, 0x20400, v4
	v_add_u32_e32 v7, -1, v2
	v_add_u32_e32 v8, 1, v2
	v_fma_f32 v9, -v7, v2, v1
	v_fma_f32 v10, -v8, v2, v1
	v_cmp_ge_f32_e64 s[6:7], 0, v9
	s_nop 1
	v_cndmask_b32_e64 v2, v2, v7, s[6:7]
	v_cmp_lt_f32_e64 s[6:7], 0, v10
	s_nop 1
	v_cndmask_b32_e64 v2, v2, v8, s[6:7]
	v_mul_f32_e32 v7, 0x37800000, v2
	v_cndmask_b32_e32 v2, v2, v7, vcc
	v_cmp_class_f32_e32 vcc, v1, v3
	v_cndmask_b32_e64 v3, v6, v5, s[0:1]
	s_nop 0
	v_cndmask_b32_e32 v2, v2, v1, vcc
	ds_write_b64 v4, v[2:3] offset:4096
	s_waitcnt vmcnt(2)
	v_mov_b32_e32 v1, v22
	v_mov_b32_e32 v6, v23
	v_mov_b32_e32 v2, 0x358637bd
	s_mov_b32 s7, 0x800000
	s_mov_b32 s6, 0xf800000
	v_mov_b32_e32 v3, 0x260
	v_fmamk_f32 v1, v1, 0x3b000000, v2
	v_fmac_f32_e32 v2, 0x3b000000, v6
	v_div_scale_f32 v4, s[0:1], v2, v2, v1
	v_rcp_f32_e32 v7, v4
	v_div_scale_f32 v5, vcc, v1, v2, v1
	v_mul_f32_e32 v6, 0x4b800000, v1
	v_fma_f32 v8, -v4, v7, 1.0
	v_fmac_f32_e32 v7, v8, v7
	v_mul_f32_e32 v8, v5, v7
	v_fma_f32 v9, -v4, v8, v5
	v_fmac_f32_e32 v8, v9, v7
	v_fma_f32 v4, -v4, v8, v5
	v_cmp_gt_f32_e64 s[0:1], s7, v1
	v_div_fmas_f32 v4, v4, v7, v8
	s_nop 0
	v_cndmask_b32_e64 v6, v1, v6, s[0:1]
	v_div_fixup_f32 v1, v4, v2, v1
	v_mul_f32_e32 v2, 0x4f800000, v1
	v_cmp_gt_f32_e32 vcc, s6, v1
	v_rsq_f32_e32 v6, v6
	v_add_u32_e32 v4, 0, v0
	v_cndmask_b32_e32 v1, v1, v2, vcc
	v_sqrt_f32_e32 v2, v1
	v_mul_f32_e32 v5, 0x45800000, v6
	v_add_u32_e32 v4, 0x20400, v4
	v_add_u32_e32 v7, -1, v2
	v_add_u32_e32 v8, 1, v2
	v_fma_f32 v9, -v7, v2, v1
	v_fma_f32 v10, -v8, v2, v1
	v_cmp_ge_f32_e64 s[6:7], 0, v9
	s_nop 1
	v_cndmask_b32_e64 v2, v2, v7, s[6:7]
	v_cmp_lt_f32_e64 s[6:7], 0, v10
	s_nop 1
	v_cndmask_b32_e64 v2, v2, v8, s[6:7]
	v_mul_f32_e32 v7, 0x37800000, v2
	v_cndmask_b32_e32 v2, v2, v7, vcc
	v_cmp_class_f32_e32 vcc, v1, v3
	v_cndmask_b32_e64 v3, v6, v5, s[0:1]
	s_nop 0
	v_cndmask_b32_e32 v2, v2, v1, vcc
	ds_write_b64 v4, v[2:3] offset:6144
	s_waitcnt vmcnt(0)
	v_mov_b32_e32 v1, v24
	v_mov_b32_e32 v6, v25
	v_mov_b32_e32 v2, 0x358637bd
	s_mov_b32 s7, 0x800000
	s_mov_b32 s6, 0xf800000
	v_mov_b32_e32 v3, 0x260
	v_fmamk_f32 v1, v1, 0x3b000000, v2
	v_fmac_f32_e32 v2, 0x3b000000, v6
	v_div_scale_f32 v4, s[0:1], v2, v2, v1
	v_rcp_f32_e32 v7, v4
	v_div_scale_f32 v5, vcc, v1, v2, v1
	v_mul_f32_e32 v6, 0x4b800000, v1
	v_fma_f32 v8, -v4, v7, 1.0
	v_fmac_f32_e32 v7, v8, v7
	v_mul_f32_e32 v8, v5, v7
	v_fma_f32 v9, -v4, v8, v5
	v_fmac_f32_e32 v8, v9, v7
	v_fma_f32 v4, -v4, v8, v5
	v_cmp_gt_f32_e64 s[0:1], s7, v1
	v_div_fmas_f32 v4, v4, v7, v8
	s_nop 0
	v_cndmask_b32_e64 v6, v1, v6, s[0:1]
	v_div_fixup_f32 v1, v4, v2, v1
	v_mul_f32_e32 v2, 0x4f800000, v1
	v_cmp_gt_f32_e32 vcc, s6, v1
	v_rsq_f32_e32 v6, v6
	v_add_u32_e32 v4, 0, v0
	v_cndmask_b32_e32 v1, v1, v2, vcc
	v_sqrt_f32_e32 v2, v1
	v_mul_f32_e32 v5, 0x45800000, v6
	v_add_u32_e32 v4, 0x20400, v4
	v_add_u32_e32 v7, -1, v2
	v_add_u32_e32 v8, 1, v2
	v_fma_f32 v9, -v7, v2, v1
	v_fma_f32 v10, -v8, v2, v1
	v_cmp_ge_f32_e64 s[6:7], 0, v9
	s_nop 1
	v_cndmask_b32_e64 v2, v2, v7, s[6:7]
	v_cmp_lt_f32_e64 s[6:7], 0, v10
	s_nop 1
	v_cndmask_b32_e64 v2, v2, v8, s[6:7]
	v_mul_f32_e32 v7, 0x37800000, v2
	v_cndmask_b32_e32 v2, v2, v7, vcc
	v_cmp_class_f32_e32 vcc, v1, v3
	v_cndmask_b32_e64 v3, v6, v5, s[0:1]
	s_nop 0
	v_cndmask_b32_e32 v2, v2, v1, vcc
	ds_write_b64 v4, v[2:3] offset:8192
	s_or_b64 exec, exec, s[4:5]
	s_branch .LBB0_786
.Lp5rs_orig:
	s_add_u32 s12, s80, 0xa0000
	s_addc_u32 s13, s81, 0
	s_movk_i32 s0, 0xff
	s_add_u32 s14, s80, 0x50000
	v_cmp_lt_u32_e64 s[2:3], s0, v164
	s_movk_i32 s0, 0x100
	s_addc_u32 s15, s81, 0
	v_cmp_gt_u32_e64 s[4:5], s0, v164
	v_lshlrev_b32_e32 v0, 3, v164
	s_and_saveexec_b64 s[16:17], s[4:5]
	s_cbranch_execz .LBB0_768
	s_lshr_b32 s0, s47, 29
	s_add_i32 s0, s33, s0
	s_and_b32 s1, s0, -8
	s_sub_i32 s1, s33, s1
	s_cmp_lt_i32 s1, 0
	s_movk_i32 s6, 0xa1
	s_cselect_b32 s6, s6, 0xa0
	s_mul_i32 s1, s1, s6
	s_ashr_i32 s0, s0, 3
	s_add_i32 s0, s1, s0
	s_ashr_i32 s1, s0, 31
	s_lshr_b32 s1, s1, 28
	s_add_i32 s1, s0, s1
	s_and_b32 s6, s1, 0xfff0
	s_sub_i32 s0, s0, s6
	s_bfe_i32 s6, s0, 0x80000
	s_bfe_u32 s6, s6, 0x2000d
	s_add_i32 s6, s0, s6
	s_and_b32 s6, s6, 0xfc
	s_sub_i32 s0, s0, s6
	s_sext_i32_i8 s0, s0
	s_lshl_b32 s1, s1, 6
	s_and_b32 s1, s1, 0xfffffc00
	s_lshl_b32 s0, s0, 8
	s_add_i32 s1, s1, s0
	v_or_b32_e32 v2, s1, v164
	v_ashrrev_i32_e32 v3, 31, v2
	v_lshlrev_b64 v[2:3], 2, v[2:3]
	v_lshl_add_u64 v[4:5], s[14:15], 0, v[2:3]
	v_lshl_add_u64 v[2:3], s[12:13], 0, v[2:3]
	s_waitcnt lgkmcnt(0)
	global_load_dword v1, v[4:5], off
	global_load_dword v6, v[2:3], off
	v_mov_b32_e32 v2, 0x358637bd
	s_mov_b32 s7, 0x800000
	s_mov_b32 s6, 0xf800000
	v_mov_b32_e32 v3, 0x260
	s_waitcnt vmcnt(0)
	v_fmamk_f32 v1, v1, 0x3b000000, v2
	v_fmac_f32_e32 v2, 0x3b000000, v6
	v_div_scale_f32 v4, s[0:1], v2, v2, v1
	v_rcp_f32_e32 v7, v4
	v_div_scale_f32 v5, vcc, v1, v2, v1
	v_mul_f32_e32 v6, 0x4b800000, v1
	v_fma_f32 v8, -v4, v7, 1.0
	v_fmac_f32_e32 v7, v8, v7
	v_mul_f32_e32 v8, v5, v7
	v_fma_f32 v9, -v4, v8, v5
	v_fmac_f32_e32 v8, v9, v7
	v_fma_f32 v4, -v4, v8, v5
	v_cmp_gt_f32_e64 s[0:1], s7, v1
	v_div_fmas_f32 v4, v4, v7, v8
	s_nop 0
	v_cndmask_b32_e64 v6, v1, v6, s[0:1]
	v_div_fixup_f32 v1, v4, v2, v1
	v_mul_f32_e32 v2, 0x4f800000, v1
	v_cmp_gt_f32_e32 vcc, s6, v1
	v_rsq_f32_e32 v6, v6
	v_add_u32_e32 v4, 0, v0
	v_cndmask_b32_e32 v1, v1, v2, vcc
	v_sqrt_f32_e32 v2, v1
	v_mul_f32_e32 v5, 0x45800000, v6
	v_add_u32_e32 v4, 0x20400, v4
	v_add_u32_e32 v7, -1, v2
	v_add_u32_e32 v8, 1, v2
	v_fma_f32 v9, -v7, v2, v1
	v_fma_f32 v10, -v8, v2, v1
	v_cmp_ge_f32_e64 s[6:7], 0, v9
	s_nop 1
	v_cndmask_b32_e64 v2, v2, v7, s[6:7]
	v_cmp_lt_f32_e64 s[6:7], 0, v10
	s_nop 1
	v_cndmask_b32_e64 v2, v2, v8, s[6:7]
	v_mul_f32_e32 v7, 0x37800000, v2
	v_cndmask_b32_e32 v2, v2, v7, vcc
	v_cmp_class_f32_e32 vcc, v1, v3
	v_cndmask_b32_e64 v3, v6, v5, s[0:1]
	s_nop 0
	v_cndmask_b32_e32 v2, v2, v1, vcc
	ds_write_b64 v4, v[2:3]

.LBB0_882:
	s_or_b64 exec, exec, s[6:7]
	s_mov_b64 s[6:7], exec
	v_mbcnt_lo_u32_b32 v0, s6, 0
	v_mbcnt_hi_u32_b32 v0, s7, v0
	v_cmp_eq_u32_e32 vcc, 0, v0
	s_waitcnt vmcnt(0)
	buffer_inv sc1
	s_and_saveexec_b64 s[8:9], vcc
	s_cbranch_execz .LBB0_884
	s_bcnt1_i32_b64 s6, s[6:7]
	v_mov_b32_e32 v0, 0x2000
	v_mov_b32_e32 v1, s6
.LBB0_884:
	s_or_b64 exec, exec, s[8:9]
	s_waitcnt vmcnt(0)

.LBB0_942:
	s_or_b64 exec, exec, s[6:7]
	s_mov_b64 s[6:7], exec
	v_mbcnt_lo_u32_b32 v0, s6, 0
	v_mbcnt_hi_u32_b32 v0, s7, v0
	v_cmp_eq_u32_e32 vcc, 0, v0
	s_waitcnt vmcnt(0)
	buffer_inv sc1
	s_and_saveexec_b64 s[8:9], vcc
	s_cbranch_execz .LBB0_944
	s_bcnt1_i32_b64 s6, s[6:7]
	v_mov_b32_e32 v0, 0x2000
	v_mov_b32_e32 v1, s6
.LBB0_944:
	s_or_b64 exec, exec, s[8:9]
	s_waitcnt vmcnt(0)

.LBB0_1013:
	s_or_b64 exec, exec, s[6:7]
	s_mov_b64 s[6:7], exec
	v_mbcnt_lo_u32_b32 v0, s6, 0
	v_mbcnt_hi_u32_b32 v0, s7, v0
	v_cmp_eq_u32_e32 vcc, 0, v0
	s_waitcnt vmcnt(0)
	buffer_inv sc1
	s_and_saveexec_b64 s[8:9], vcc
	s_cbranch_execz .LBB0_1015
	s_bcnt1_i32_b64 s6, s[6:7]
	v_mov_b32_e32 v0, 0x2000
	v_mov_b32_e32 v1, s6
.LBB0_1015:
	s_or_b64 exec, exec, s[8:9]
	s_waitcnt vmcnt(0)
